# attention epilogue: gate loads issued together and early, head gains from LDS; K/V register prefetch one tile earlier; P4 epilogue row-scale loads batched
# speedup vs baseline: 1.0344x; 1.0344x over previous
; #define LAS __attribute__((address_space(3)))
; __device__ __forceinline__ void attn_phase(const Params& P, LAS unsigned char* lds, int bx, int tid_in) {
;     int tid = tid_in; asm volatile("" : "+v"(tid)); const int lane = tid & 63, wave = __builtin_amdgcn_readfirstlane(tid >> 6);
;     unsigned char* ws = P.ws;
;     bf16_t* Q = (bf16_t*)(ws + WS_Q); const bf16_t* K = (const bf16_t*)(ws + WS_K); const bf16_t* Vt = (const bf16_t*)(ws + WS_V); const bf16_t* Z = (const bf16_t*)P.out;
;     const float* tab = (const float*)(ws + WS_MISC + MISC_ATT);
;     const float lam = __builtin_bit_cast(float, __builtin_amdgcn_readfirstlane(__builtin_bit_cast(int, tab[32]))), SB = __builtin_bit_cast(float, __builtin_amdgcn_readfirstlane(__builtin_bit_cast(int, tab[33])));
;     unsigned* qctr = (unsigned*)(ws + WS_MISC + MISC_ATQ) + 64 * (bx & 7);
;     volatile LAS int* slot = (volatile LAS int*)(lds + 2 * KT_BYTES + 2 * VT_BYTES);
;     const int b = bx & 7;
;     int unext = 0; if (tid == 0) unext = (int)atomicAdd(qctr, 1u);
.LBB0_233:
	s_or_b64 exec, exec, s[6:7]
	v_mov_b32_e32 v0, v215
	v_mov_b32_e32 v1, 0x1e830000
	s_barrier
	v_and_b32_e32 v137, 63, v215
	v_lshlrev_b32_e32 v137, 4, v137
	v_cmp_gt_u32_e32 vcc, 0x200, v137
	s_and_saveexec_b64 s[10:11], vcc
	global_load_dwordx4 v[138:141], v137, s[54:55]
	v_add_u32_e32 v137, 0x11100, v137
	s_waitcnt vmcnt(0)
	ds_write_b128 v137, v[138:141]
	s_waitcnt lgkmcnt(0)
	s_or_b64 exec, exec, s[10:11]
	global_load_dwordx2 v[2:3], v1, s[30:31] offset:128
	v_lshl_add_u64 v[4:5], v[208:209], 2, s[30:31]
	s_mov_b64 s[6:7], 0x1e820000
	v_mov_b32_e32 v211, 0
	v_lshl_add_u64 v[212:213], v[4:5], 0, s[6:7]
	v_readfirstlane_b32 s10, v0
	v_cmp_eq_u32_e64 s[6:7], 0, v0
	v_mov_b32_e32 v229, 0
	s_waitcnt vmcnt(0)
	v_readfirstlane_b32 s71, v2
	v_readfirstlane_b32 s72, v3
	s_and_saveexec_b64 s[8:9], s[6:7]
	s_cbranch_execz .LBB0_235
	v_mov_b32_e32 v1, 1
	global_atomic_add v229, v[212:213], v1, off sc0

; __device__ __forceinline__ void attn_unit(int b, int h, int qb, bf16_t* Q, const bf16_t* __restrict__ K, const bf16_t* __restrict__ Vt, const bf16_t* __restrict__ Z, const float* __restrict__ hg, float lam, ...
;     ...
;     const float l1 = lsum[0] + __shfl_xor(lsum[0], 32), l2 = lsum[1] + __shfl_xor(lsum[1], 32);
;     const float i1 = 1.f / l1, i2 = lam / l2;
;     float ss = 0.f;
; #pragma unroll
;     for (int d = 0; d < 4; ++d)
; #pragma unroll
;         for (int r = 0; r < 16; ++r) { const float v = o[0][d][r] * i1 - o[1][d][r] * i2; o[0][d][r] = v; ss += v * v; }
;     ...
;     const size_t off = (rowbase + qw0 + (lane_l & 31)) * BR + h * 128 + 4 * (lane_l >> 5);
;     __builtin_amdgcn_sched_barrier(0);
;     const int hi_l = lane_l >> 5;
;     const size_t offw = off - 4 * hi_l;
; #pragma unroll
;     for (int d = 0; d < 4; ++d)
; #pragma unroll
;         for (int ip = 0; ip < 2; ++ip) { __builtin_amdgcn_sched_barrier(0);
;             u32x2 w[2];
;             const u32x4 zl = *(const u32x4*)(Z + offw + 32 * d + 16 * ip + 8 * hi_l);
.LBB0_236:
	v_ashrrev_i32_e32 v138, 5, v230
	v_and_or_b32 v140, v230, 31, s82
	v_mov_b32_e32 v141, s83
	v_lshlrev_b64 v[140:141], 11, v[140:141]
	v_lshl_add_u64 v[140:141], v[140:141], 0, s[18:19]
	v_lshlrev_b32_e32 v138, 3, v138
	v_lshlrev_b64 v[140:141], 1, v[140:141]
	v_ashrrev_i32_e32 v139, 31, v138
	v_lshl_add_u64 v[140:141], s[28:29], 0, v[140:141]
	v_lshlrev_b64 v[138:139], 1, v[138:139]
	v_lshl_add_u64 v[140:141], v[140:141], 0, v[138:139]
	global_load_dwordx4 v[146:149], v[140:141], off
	global_load_dwordx4 v[150:153], v[140:141], off offset:32
	global_load_dwordx4 v[154:157], v[140:141], off offset:64
	global_load_dwordx4 v[158:161], v[140:141], off offset:96
	global_load_dwordx4 v[162:165], v[140:141], off offset:128
	global_load_dwordx4 v[166:169], v[140:141], off offset:160
	global_load_dwordx4 v[170:173], v[140:141], off offset:192
	global_load_dwordx4 v[174:177], v[140:141], off offset:224
	ds_bpermute_b32 v128, v217, v224
	ds_bpermute_b32 v129, v217, v225
	s_waitcnt lgkmcnt(0)
	v_pk_add_f32 v[128:129], v[224:225], v[128:129]
	s_nop 0
	v_div_scale_f32 v130, s[8:9], v129, v129, s71
	v_rcp_f32_e32 v132, v130
	v_div_scale_f32 v131, vcc, s71, v129, s71
	v_div_scale_f32 v133, s[8:9], v128, v128, 1.0
	v_fma_f32 v135, -v130, v132, 1.0
	v_fmac_f32_e32 v132, v135, v132
	v_mul_f32_e32 v135, v131, v132
	v_rcp_f32_e32 v134, v133
	v_fma_f32 v136, -v130, v135, v131
	v_fmac_f32_e32 v135, v136, v132
	v_fma_f32 v130, -v130, v135, v131
	v_div_fmas_f32 v130, v130, v132, v135
	v_div_fixup_f32 v129, v130, v129, s71
	v_fma_f32 v130, -v133, v134, 1.0
	v_fmac_f32_e32 v134, v130, v134
	v_div_scale_f32 v130, vcc, 1.0, v128, 1.0
	v_mul_f32_e32 v131, v130, v134
	v_fma_f32 v132, -v133, v131, v130
	v_fmac_f32_e32 v131, v132, v134
	v_fma_f32 v130, -v133, v131, v130
	v_div_fmas_f32 v130, v130, v134, v131
	v_div_fixup_f32 v128, v130, v128, 1.0
	v_mov_b32_e32 v131, v112
	v_mov_b32_e32 v112, v65
	v_mov_b32_e32 v130, v64
	v_pk_mul_f32 v[64:65], v[112:113], v[128:129]
	v_pk_mul_f32 v[130:131], v[130:131], v[128:129]
	v_sub_f32_e32 v132, v64, v65
	v_mov_b32_e32 v64, v66
	v_mov_b32_e32 v65, v114
	v_pk_mul_f32 v[64:65], v[64:65], v[128:129]
	v_mov_b32_e32 v114, v67
	v_sub_f32_e32 v133, v64, v65
	v_pk_mul_f32 v[64:65], v[114:115], v[128:129]
	v_sub_f32_e32 v131, v130, v131
	v_sub_f32_e32 v134, v64, v65
	v_mov_b32_e32 v64, v68
	v_mov_b32_e32 v65, v116
	v_pk_mul_f32 v[64:65], v[64:65], v[128:129]
	v_mov_b32_e32 v116, v69
	v_sub_f32_e32 v135, v64, v65
	v_pk_mul_f32 v[64:65], v[116:117], v[128:129]
	s_nop 0
	v_sub_f32_e32 v136, v64, v65
	v_mov_b32_e32 v64, v70
	v_mov_b32_e32 v65, v118
	v_pk_mul_f32 v[64:65], v[64:65], v[128:129]
	v_mov_b32_e32 v118, v71
	v_sub_f32_e32 v130, v64, v65
	v_pk_mul_f32 v[64:65], v[118:119], v[128:129]
	s_nop 0
	v_sub_f32_e32 v119, v64, v65
	v_mov_b32_e32 v64, v72
	v_mov_b32_e32 v65, v120
	v_pk_mul_f32 v[64:65], v[64:65], v[128:129]
	v_mov_b32_e32 v120, v73
	v_sub_f32_e32 v118, v64, v65
	v_pk_mul_f32 v[64:65], v[120:121], v[128:129]
	s_nop 0
	v_sub_f32_e32 v117, v64, v65
	v_mov_b32_e32 v64, v74
	v_mov_b32_e32 v65, v122
	v_pk_mul_f32 v[64:65], v[64:65], v[128:129]
	v_mov_b32_e32 v122, v75
	v_sub_f32_e32 v116, v64, v65
	v_pk_mul_f32 v[64:65], v[122:123], v[128:129]
	s_nop 0
	v_sub_f32_e32 v115, v64, v65
	v_mov_b32_e32 v64, v76
	v_mov_b32_e32 v65, v124
	v_pk_mul_f32 v[64:65], v[64:65], v[128:129]
	v_mov_b32_e32 v124, v77
	v_sub_f32_e32 v114, v64, v65
	v_pk_mul_f32 v[64:65], v[124:125], v[128:129]
	s_nop 0
	v_sub_f32_e32 v113, v64, v65
	v_mov_b32_e32 v64, v78
	v_mov_b32_e32 v65, v126
	v_pk_mul_f32 v[64:65], v[64:65], v[128:129]
	v_mov_b32_e32 v126, v79
	v_sub_f32_e32 v112, v64, v65
	v_pk_mul_f32 v[64:65], v[126:127], v[128:129]
	s_nop 0
	v_sub_f32_e32 v78, v64, v65
	v_mov_b32_e32 v65, v96
	v_mov_b32_e32 v96, v49
	v_mov_b32_e32 v64, v48
	v_pk_mul_f32 v[48:49], v[96:97], v[128:129]
	v_pk_mul_f32 v[64:65], v[64:65], v[128:129]
	v_sub_f32_e32 v76, v48, v49
	v_mov_b32_e32 v48, v50
	v_mov_b32_e32 v49, v98
	v_pk_mul_f32 v[48:49], v[48:49], v[128:129]
	v_mov_b32_e32 v98, v51
	v_sub_f32_e32 v75, v48, v49
	v_pk_mul_f32 v[48:49], v[98:99], v[128:129]
	v_sub_f32_e32 v77, v64, v65
	v_sub_f32_e32 v74, v48, v49
	v_mov_b32_e32 v48, v52
	v_mov_b32_e32 v49, v100
	v_pk_mul_f32 v[48:49], v[48:49], v[128:129]
	v_mov_b32_e32 v100, v53
	v_sub_f32_e32 v73, v48, v49
	v_pk_mul_f32 v[48:49], v[100:101], v[128:129]
	s_nop 0
	v_sub_f32_e32 v72, v48, v49
	v_mov_b32_e32 v48, v54
	v_mov_b32_e32 v49, v102
	v_pk_mul_f32 v[48:49], v[48:49], v[128:129]
	v_mov_b32_e32 v102, v55
	v_sub_f32_e32 v71, v48, v49
	v_pk_mul_f32 v[48:49], v[102:103], v[128:129]
	s_nop 0
	v_sub_f32_e32 v70, v48, v49
	v_mov_b32_e32 v48, v56
	v_mov_b32_e32 v49, v104
	v_pk_mul_f32 v[48:49], v[48:49], v[128:129]
	v_mov_b32_e32 v104, v57
	v_sub_f32_e32 v69, v48, v49
	v_pk_mul_f32 v[48:49], v[104:105], v[128:129]
	s_nop 0
	v_sub_f32_e32 v68, v48, v49
	v_mov_b32_e32 v48, v58
	v_mov_b32_e32 v49, v106
	v_pk_mul_f32 v[48:49], v[48:49], v[128:129]
	v_mov_b32_e32 v106, v59
	v_sub_f32_e32 v67, v48, v49
	v_pk_mul_f32 v[48:49], v[106:107], v[128:129]
	s_nop 0
	v_sub_f32_e32 v66, v48, v49
	v_mov_b32_e32 v48, v60
	v_mov_b32_e32 v49, v108
	v_pk_mul_f32 v[48:49], v[48:49], v[128:129]
	v_mov_b32_e32 v108, v61
	v_sub_f32_e32 v65, v48, v49
	v_pk_mul_f32 v[48:49], v[108:109], v[128:129]
	s_nop 0
	v_sub_f32_e32 v64, v48, v49
	v_mov_b32_e32 v48, v62
	v_mov_b32_e32 v49, v110
	v_pk_mul_f32 v[48:49], v[48:49], v[128:129]
	v_mov_b32_e32 v110, v63
	v_sub_f32_e32 v61, v48, v49
	v_pk_mul_f32 v[48:49], v[110:111], v[128:129]
	s_nop 0
	v_sub_f32_e32 v60, v48, v49
	v_mov_b32_e32 v49, v80
	v_mov_b32_e32 v80, v17
	v_mov_b32_e32 v48, v16
; __device__ __forceinline__ void attn_unit(int b, int h, int qb, bf16_t* Q, const bf16_t* __restrict__ K, const bf16_t* __restrict__ Vt, const bf16_t* __restrict__ Z, const float* __restrict__ hg, float lam, ...
;     ...
;     float ss = 0.f;
; #pragma unroll
;     for (int d = 0; d < 4; ++d)
; #pragma unroll
;         for (int r = 0; r < 16; ++r) { const float v = o[0][d][r] * i1 - o[1][d][r] * i2; o[0][d][r] = v; ss += v * v; }
;     ss += __shfl_xor(ss, 32);
;     const float rs = rsqrtf(ss * (1.f / 128.f) + EPS) * (1.f - LAM0);
	v_pk_mul_f32 v[16:17], v[80:81], v[128:129]
	v_pk_mul_f32 v[48:49], v[48:49], v[128:129]
	v_sub_f32_e32 v58, v16, v17
	v_mov_b32_e32 v16, v18
	v_mov_b32_e32 v17, v82
	v_pk_mul_f32 v[16:17], v[16:17], v[128:129]
	v_mov_b32_e32 v82, v19
	v_sub_f32_e32 v57, v16, v17
	v_pk_mul_f32 v[16:17], v[82:83], v[128:129]
	v_sub_f32_e32 v59, v48, v49
	v_sub_f32_e32 v56, v16, v17
	v_mov_b32_e32 v16, v20
	v_mov_b32_e32 v17, v84
	v_pk_mul_f32 v[16:17], v[16:17], v[128:129]
	v_mov_b32_e32 v84, v21
	v_sub_f32_e32 v55, v16, v17
	v_pk_mul_f32 v[16:17], v[84:85], v[128:129]
	s_nop 0
	v_sub_f32_e32 v54, v16, v17
	v_mov_b32_e32 v16, v22
	v_mov_b32_e32 v17, v86
	v_pk_mul_f32 v[16:17], v[16:17], v[128:129]
	v_mov_b32_e32 v86, v23
	v_sub_f32_e32 v53, v16, v17
	v_pk_mul_f32 v[16:17], v[86:87], v[128:129]
	s_nop 0
	v_sub_f32_e32 v52, v16, v17
	v_mov_b32_e32 v16, v24
	v_mov_b32_e32 v17, v88
	v_pk_mul_f32 v[16:17], v[16:17], v[128:129]
	v_mov_b32_e32 v88, v25
	v_sub_f32_e32 v51, v16, v17
	v_pk_mul_f32 v[16:17], v[88:89], v[128:129]
	s_nop 0
	v_sub_f32_e32 v50, v16, v17
	v_mov_b32_e32 v16, v26
	v_mov_b32_e32 v17, v90
	v_pk_mul_f32 v[16:17], v[16:17], v[128:129]
	v_mov_b32_e32 v90, v27
	v_sub_f32_e32 v49, v16, v17
	v_pk_mul_f32 v[16:17], v[90:91], v[128:129]
	s_nop 0
	v_sub_f32_e32 v48, v16, v17
	v_mov_b32_e32 v16, v28
	v_mov_b32_e32 v17, v92
	v_pk_mul_f32 v[16:17], v[16:17], v[128:129]
	v_mov_b32_e32 v92, v29
	v_sub_f32_e32 v27, v16, v17
	v_pk_mul_f32 v[16:17], v[92:93], v[128:129]
	s_nop 0
	v_sub_f32_e32 v26, v16, v17
	v_mov_b32_e32 v16, v30
	v_mul_f32_e32 v30, v131, v131
	v_fmac_f32_e32 v30, v132, v132
	v_fmac_f32_e32 v30, v133, v133
	v_fmac_f32_e32 v30, v134, v134
	v_fmac_f32_e32 v30, v135, v135
	v_fmac_f32_e32 v30, v136, v136
	v_fmac_f32_e32 v30, v130, v130
	v_fmac_f32_e32 v30, v119, v119
	v_fmac_f32_e32 v30, v118, v118
	v_fmac_f32_e32 v30, v117, v117
	v_fmac_f32_e32 v30, v116, v116
	v_fmac_f32_e32 v30, v115, v115
	v_fmac_f32_e32 v30, v114, v114
	v_fmac_f32_e32 v30, v113, v113
	v_fmac_f32_e32 v30, v112, v112
	v_fmac_f32_e32 v30, v78, v78
	v_fmac_f32_e32 v30, v77, v77
	v_fmac_f32_e32 v30, v76, v76
	v_fmac_f32_e32 v30, v75, v75
	v_fmac_f32_e32 v30, v74, v74
	v_fmac_f32_e32 v30, v73, v73
	v_fmac_f32_e32 v30, v72, v72
	v_fmac_f32_e32 v30, v71, v71
	v_fmac_f32_e32 v30, v70, v70
	v_fmac_f32_e32 v30, v69, v69
	v_fmac_f32_e32 v30, v68, v68
	v_fmac_f32_e32 v30, v67, v67
	v_fmac_f32_e32 v30, v66, v66
	v_fmac_f32_e32 v30, v65, v65
	v_fmac_f32_e32 v30, v64, v64
	v_fmac_f32_e32 v30, v61, v61
	v_fmac_f32_e32 v30, v60, v60
	v_fmac_f32_e32 v30, v59, v59
	v_fmac_f32_e32 v30, v58, v58
	v_fmac_f32_e32 v30, v57, v57
	v_fmac_f32_e32 v30, v56, v56
	v_mov_b32_e32 v17, v94
	v_fmac_f32_e32 v30, v55, v55
	v_pk_mul_f32 v[16:17], v[16:17], v[128:129]
	v_mov_b32_e32 v94, v31
	v_fmac_f32_e32 v30, v54, v54
	v_sub_f32_e32 v25, v16, v17
	v_pk_mul_f32 v[16:17], v[94:95], v[128:129]
	v_fmac_f32_e32 v30, v53, v53
	v_sub_f32_e32 v24, v16, v17
	v_mov_b32_e32 v17, v32
	v_mov_b32_e32 v32, v1
	v_fmac_f32_e32 v30, v52, v52
	v_mov_b32_e32 v16, v0
	v_pk_mul_f32 v[0:1], v[32:33], v[128:129]
	v_fmac_f32_e32 v30, v51, v51
	v_sub_f32_e32 v22, v0, v1
	v_mov_b32_e32 v0, v2
	v_mov_b32_e32 v1, v34
	v_fmac_f32_e32 v30, v50, v50
	v_pk_mul_f32 v[0:1], v[0:1], v[128:129]
	v_mov_b32_e32 v34, v3
	v_fmac_f32_e32 v30, v49, v49
	v_sub_f32_e32 v21, v0, v1
	v_pk_mul_f32 v[0:1], v[34:35], v[128:129]
	v_fmac_f32_e32 v30, v48, v48
	v_sub_f32_e32 v20, v0, v1
	v_mov_b32_e32 v0, v4
	v_mov_b32_e32 v1, v36
	v_fmac_f32_e32 v30, v27, v27
	v_pk_mul_f32 v[0:1], v[0:1], v[128:129]
	v_mov_b32_e32 v36, v5
	v_fmac_f32_e32 v30, v26, v26
	v_pk_mul_f32 v[16:17], v[16:17], v[128:129]
	v_sub_f32_e32 v19, v0, v1
	v_pk_mul_f32 v[0:1], v[36:37], v[128:129]
	v_fmac_f32_e32 v30, v25, v25
	v_sub_f32_e32 v23, v16, v17
	v_sub_f32_e32 v18, v0, v1
	v_mov_b32_e32 v0, v6
	v_mov_b32_e32 v1, v38
	v_mov_b32_e32 v38, v7
	v_fmac_f32_e32 v30, v24, v24
	v_pk_mul_f32 v[0:1], v[0:1], v[128:129]
	v_pk_mul_f32 v[2:3], v[38:39], v[128:129]
	v_fmac_f32_e32 v30, v23, v23
	v_mov_b32_e32 v4, v2
	v_mov_b32_e32 v5, v0
	v_mov_b32_e32 v0, v3
	v_fmac_f32_e32 v30, v22, v22
	v_pk_add_f32 v[16:17], v[4:5], v[0:1] neg_lo:[0,1] neg_hi:[0,1]
	v_mov_b32_e32 v0, v8
	v_mov_b32_e32 v1, v40
	v_mov_b32_e32 v40, v9
	v_fmac_f32_e32 v30, v21, v21
	v_pk_mul_f32 v[0:1], v[0:1], v[128:129]
	v_pk_mul_f32 v[2:3], v[40:41], v[128:129]
	v_fmac_f32_e32 v30, v20, v20
	v_mov_b32_e32 v4, v2
	v_mov_b32_e32 v5, v0
	v_mov_b32_e32 v0, v3
	v_fmac_f32_e32 v30, v19, v19
	v_pk_mul_f32 v[28:29], v[16:17], v[16:17]
	v_pk_add_f32 v[6:7], v[4:5], v[0:1] neg_lo:[0,1] neg_hi:[0,1]
	v_mov_b32_e32 v0, v10
	v_mov_b32_e32 v1, v42
	v_mov_b32_e32 v42, v11
	v_fmac_f32_e32 v30, v18, v18
	v_pk_mul_f32 v[0:1], v[0:1], v[128:129]
	v_pk_mul_f32 v[2:3], v[42:43], v[128:129]
	v_add_f32_e32 v29, v29, v30
	v_pk_mul_f32 v[8:9], v[6:7], v[6:7]
	v_mov_b32_e32 v4, v2
	v_mov_b32_e32 v5, v0
	v_mov_b32_e32 v0, v3
	v_add_f32_e32 v28, v28, v29
	v_pk_add_f32 v[4:5], v[4:5], v[0:1] neg_lo:[0,1] neg_hi:[0,1]
	v_mov_b32_e32 v0, v129
	v_add_f32_e32 v9, v9, v28
	v_pk_mul_f32 v[10:11], v[4:5], v[4:5]
	v_pk_mul_f32 v[2:3], v[44:45], v[0:1] op_sel_hi:[1,0]
	v_add_f32_e32 v8, v8, v9
	v_pk_fma_f32 v[2:3], v[12:13], v[128:129], v[2:3] op_sel_hi:[1,0,1] neg_lo:[0,0,1] neg_hi:[0,0,1]
	v_add_f32_e32 v8, v11, v8
	v_pk_mul_f32 v[12:13], v[2:3], v[2:3]
	v_pk_mul_f32 v[0:1], v[46:47], v[0:1] op_sel_hi:[1,0]
	v_add_f32_e32 v8, v10, v8
	v_pk_fma_f32 v[0:1], v[14:15], v[128:129], v[0:1] op_sel_hi:[1,0,1] neg_lo:[0,0,1] neg_hi:[0,0,1]
	v_add_f32_e32 v8, v12, v8
	v_pk_mul_f32 v[14:15], v[0:1], v[0:1]
	v_add_f32_e32 v8, v13, v8
	v_add_f32_e32 v8, v14, v8
	v_add_f32_e32 v8, v15, v8
	ds_bpermute_b32 v9, v217, v8
	v_mov_b32_e32 v15, v230
	s_waitcnt lgkmcnt(0)
; __device__ __forceinline__ unsigned pk2(float lo, float hi) { return pg8::cvt_pk_bf16(lo, hi); }
; __device__ __forceinline__ float siluf_(float v) { return v * __builtin_amdgcn_rcpf(1.f + __builtin_amdgcn_exp2f(-LOG2E * v)); }
; __device__ __forceinline__ void attn_unit(int b, int h, int qb, bf16_t* Q, const bf16_t* __restrict__ K, const bf16_t* __restrict__ Vt, const bf16_t* __restrict__ Z, const float* __restrict__ hg, float lam, ...
;     ...
;     const float rs = rsqrtf(ss * (1.f / 128.f) + EPS) * (1.f - LAM0);
;     int lane_l = lane; asm volatile("" : "+v"(lane_l));
;     const size_t off = (rowbase + qw0 + (lane_l & 31)) * BR + h * 128 + 4 * (lane_l >> 5);
;     __builtin_amdgcn_sched_barrier(0);
;     const int hi_l = lane_l >> 5;
;     const size_t offw = off - 4 * hi_l;
; #pragma unroll
;     for (int d = 0; d < 4; ++d)
; #pragma unroll
;         for (int ip = 0; ip < 2; ++ip) { __builtin_amdgcn_sched_barrier(0);
;             u32x2 w[2];
;             const u32x4 zl = *(const u32x4*)(Z + offw + 32 * d + 16 * ip + 8 * hi_l);
;             const unsigned zsx = hi_l ? zl.x : zl.z, zsy = hi_l ? zl.y : zl.w;
;             const unsigned zrx = __shfl_xor(zsx, 32), zry = __shfl_xor(zsy, 32);
; #pragma unroll
;             for (int k = 0; k < 2; ++k) { const int i = 2 * ip + k, e = 32 * d + 8 * i;
;                 const f32x4 g4 = *(const f32x4*)(hg + e + 4 * hi_l);
;                 const u32x2 z2 = (k == 0) ? (hi_l ? (u32x2){zrx, zry} : (u32x2){zl.x, zl.y}) : (hi_l ? (u32x2){zl.z, zl.w} : (u32x2){zrx, zry});
;                 const float v0 = o[0][d][4 * i] * rs * g4[0] * siluf_(bflo(z2.x)), v1 = o[0][d][4 * i + 1] * rs * g4[1] * siluf_(bfhi(z2.x));
;                 const float v2 = o[0][d][4 * i + 2] * rs * g4[2] * siluf_(bflo(z2.y)), v3 = o[0][d][4 * i + 3] * rs * g4[3] * siluf_(bfhi(z2.y));
;                 w[k] = (u32x2){pk2(v0, v1), pk2(v2, v3)}; }
;             const u32x2 snd = hi_l ? w[0] : w[1];
;             const unsigned rx = __shfl_xor(snd.x, 32), ry = __shfl_xor(snd.y, 32);
;             const u32x4 st = hi_l ? (u32x4){rx, ry, w[1].x, w[1].y} : (u32x4){w[0].x, w[0].y, rx, ry};
;             *(u32x4*)(Q + offw + 32 * d + 16 * ip + 8 * hi_l) = st; }
	v_add_f32_e32 v8, v8, v9
	v_fmamk_f32 v8, v8, 0x3c000000, v245
	v_mul_f32_e32 v9, 0x4b800000, v8
	v_cmp_gt_f32_e32 vcc, s81, v8
	v_ashrrev_i32_e32 v28, 5, v15
	v_lshlrev_b32_e32 v137, 4, v28
	v_add_u32_e32 v137, 0x11100, v137
	v_lshlrev_b32_e32 v10, 2, v28
	v_cndmask_b32_e32 v8, v8, v9, vcc
	v_rsq_f32_e32 v8, v8
	v_ashrrev_i32_e32 v11, 31, v10
	v_mul_f32_e32 v9, 0x45800000, v8
	v_cndmask_b32_e32 v8, v8, v9, vcc
	v_mul_f32_e32 v14, 0x3f4ccccd, v8
	v_and_or_b32 v8, v15, 31, s82
	v_mov_b32_e32 v9, s83
	v_lshlrev_b64 v[8:9], 11, v[8:9]
	v_lshl_add_u64 v[8:9], v[8:9], 0, s[18:19]
	v_lshlrev_b32_e32 v28, 3, v28
	v_lshlrev_b64 v[8:9], 1, v[8:9]
	v_ashrrev_i32_e32 v29, 31, v28
	v_lshl_add_u64 v[12:13], s[28:29], 0, v[8:9]
	v_lshlrev_b64 v[28:29], 1, v[28:29]
	v_lshl_add_u64 v[8:9], s[34:35], 0, v[8:9]
	v_lshl_add_u64 v[12:13], v[12:13], 0, v[28:29]
	v_cmp_gt_u32_e32 vcc, 32, v15
	v_lshl_add_u64 v[10:11], v[10:11], 2, s[54:55]
	v_lshl_add_u64 v[8:9], v[8:9], 0, v[28:29]
	ds_read_b128 v[32:35], v137
	v_mul_f32_e32 v37, v131, v14
	v_mul_f32_e32 v39, v132, v14
	v_mul_f32_e32 v41, v133, v14
	v_mul_f32_e32 v43, v134, v14
	s_waitcnt vmcnt(7)
	v_mov_b32_e32 v28, v146
	v_mov_b32_e32 v29, v147
	v_mov_b32_e32 v30, v148
	v_mov_b32_e32 v31, v149
	v_cndmask_b32_e32 v15, v28, v30, vcc
	v_cndmask_b32_e32 v36, v29, v31, vcc
	ds_bpermute_b32 v62, v217, v36
	ds_bpermute_b32 v15, v217, v15
	s_waitcnt lgkmcnt(0)
	v_mov_b32_e32 v45, v32
	v_mov_b32_e32 v47, v34
	s_waitcnt lgkmcnt(1)
	v_cndmask_b32_e32 v29, v62, v29, vcc
	s_waitcnt lgkmcnt(0)
	v_cndmask_b32_e32 v28, v15, v28, vcc
	v_lshlrev_b32_e32 v36, 16, v28
	v_and_b32_e32 v38, 0xffff0000, v28
	v_lshlrev_b32_e32 v40, 16, v29
	v_and_b32_e32 v42, 0xffff0000, v29
	v_mul_f32_e32 v28, 0xbfb8aa3b, v36
	v_mul_f32_e32 v29, 0xbfb8aa3b, v38
	v_mul_f32_e32 v32, 0xbfb8aa3b, v40
	v_mul_f32_e32 v34, 0xbfb8aa3b, v42
	v_exp_f32_e32 v28, v28
	v_exp_f32_e32 v29, v29
	v_exp_f32_e32 v32, v32
	v_exp_f32_e32 v34, v34
	v_add_f32_e32 v28, 1.0, v28
	v_add_f32_e32 v29, 1.0, v29
	v_add_f32_e32 v46, 1.0, v32
	v_add_f32_e32 v34, 1.0, v34
	v_rcp_f32_e32 v44, v28
	v_rcp_f32_e32 v32, v29
	v_rcp_f32_e32 v46, v46
	v_rcp_f32_e32 v34, v34
	v_pk_mul_f32 v[28:29], v[44:45], v[36:37]
	v_pk_mul_f32 v[32:33], v[32:33], v[38:39]
	v_pk_mul_f32 v[36:37], v[46:47], v[40:41]
	v_pk_mul_f32 v[34:35], v[34:35], v[42:43]
	v_mul_f32_e32 v28, v28, v29
	v_mul_f32_e32 v29, v32, v33
	v_mul_f32_e32 v32, v36, v37
	v_mul_f32_e32 v33, v34, v35
	v_cvt_pk_bf16_f32 v44, v28, v29
	v_cvt_pk_bf16_f32 v45, v32, v33
	ds_read_b128 v[32:35], v137 offset:32
	v_cndmask_b32_e32 v31, v31, v62, vcc
	v_cndmask_b32_e32 v15, v30, v15, vcc
	v_lshlrev_b32_e32 v28, 16, v15
	v_lshlrev_b32_e32 v38, 16, v31
	v_and_b32_e32 v36, 0xffff0000, v15
	v_and_b32_e32 v40, 0xffff0000, v31
	v_mul_f32_e32 v15, 0xbfb8aa3b, v28
	v_mul_f32_e32 v31, 0xbfb8aa3b, v38
	v_mul_f32_e32 v30, 0xbfb8aa3b, v36
	v_mul_f32_e32 v42, 0xbfb8aa3b, v40
	v_exp_f32_e32 v15, v15
	v_exp_f32_e32 v31, v31
	v_exp_f32_e32 v30, v30
	v_exp_f32_e32 v42, v42
	v_add_f32_e32 v15, 1.0, v15
	v_add_f32_e32 v31, 1.0, v31
	v_add_f32_e32 v43, 1.0, v30
	v_add_f32_e32 v46, 1.0, v42
	v_rcp_f32_e32 v30, v15
	v_rcp_f32_e32 v42, v31
	v_mul_f32_e32 v29, v135, v14
	v_mul_f32_e32 v39, v130, v14
	v_mul_f32_e32 v37, v136, v14
	v_mul_f32_e32 v41, v119, v14
	s_waitcnt lgkmcnt(0)
	v_mov_b32_e32 v31, v32
	v_rcp_f32_e32 v32, v43
	v_mov_b32_e32 v43, v34
	v_rcp_f32_e32 v34, v46
	v_pk_mul_f32 v[28:29], v[30:31], v[28:29]
	v_pk_mul_f32 v[30:31], v[42:43], v[38:39]
	v_mul_f32_e32 v15, v28, v29
	v_mul_f32_e32 v38, v30, v31
	v_pk_mul_f32 v[28:29], v[32:33], v[36:37]
	v_pk_mul_f32 v[30:31], v[34:35], v[40:41]
	v_mul_f32_e32 v28, v28, v29
	v_mul_f32_e32 v29, v30, v31
	v_cvt_pk_bf16_f32 v15, v15, v28
	v_cvt_pk_bf16_f32 v29, v38, v29
	s_nop 0
	v_cndmask_b32_e32 v28, v44, v15, vcc
	v_cndmask_b32_e32 v30, v45, v29, vcc
	ds_bpermute_b32 v28, v217, v28
	ds_bpermute_b32 v32, v217, v30
	s_waitcnt lgkmcnt(1)
	v_cndmask_b32_e32 v30, v15, v28, vcc
	v_cndmask_b32_e32 v28, v28, v44, vcc
	s_waitcnt lgkmcnt(0)
	v_cndmask_b32_e32 v31, v29, v32, vcc
	v_cndmask_b32_e32 v29, v32, v45, vcc
	global_store_dwordx4 v[8:9], v[28:31], off
	s_nop 0
	ds_read_b128 v[32:35], v137 offset:64
	v_mul_f32_e32 v37, v118, v14
	v_mul_f32_e32 v39, v117, v14
	v_mul_f32_e32 v41, v116, v14
	v_mul_f32_e32 v43, v115, v14
	s_waitcnt vmcnt(7)
	v_mov_b32_e32 v28, v150
	v_mov_b32_e32 v29, v151
	v_mov_b32_e32 v30, v152
	v_mov_b32_e32 v31, v153
	v_cndmask_b32_e32 v15, v28, v30, vcc
	v_cndmask_b32_e32 v36, v29, v31, vcc
	ds_bpermute_b32 v62, v217, v36
	ds_bpermute_b32 v15, v217, v15
	s_waitcnt lgkmcnt(0)
	v_mov_b32_e32 v45, v32
	v_mov_b32_e32 v47, v34
	s_waitcnt lgkmcnt(1)
	v_cndmask_b32_e32 v29, v62, v29, vcc
	s_waitcnt lgkmcnt(0)
	v_cndmask_b32_e32 v28, v15, v28, vcc
	v_lshlrev_b32_e32 v36, 16, v28
	v_and_b32_e32 v38, 0xffff0000, v28
	v_lshlrev_b32_e32 v40, 16, v29
	v_and_b32_e32 v42, 0xffff0000, v29
	v_mul_f32_e32 v28, 0xbfb8aa3b, v36
	v_mul_f32_e32 v29, 0xbfb8aa3b, v38
	v_mul_f32_e32 v32, 0xbfb8aa3b, v40
	v_mul_f32_e32 v34, 0xbfb8aa3b, v42
	v_exp_f32_e32 v28, v28
	v_exp_f32_e32 v29, v29
	v_exp_f32_e32 v32, v32
	v_exp_f32_e32 v34, v34
	v_add_f32_e32 v28, 1.0, v28
	v_add_f32_e32 v29, 1.0, v29
	v_add_f32_e32 v46, 1.0, v32
	v_add_f32_e32 v34, 1.0, v34
	v_rcp_f32_e32 v44, v28
	v_rcp_f32_e32 v32, v29
	v_rcp_f32_e32 v46, v46
	v_rcp_f32_e32 v34, v34
	v_pk_mul_f32 v[28:29], v[44:45], v[36:37]
	v_pk_mul_f32 v[32:33], v[32:33], v[38:39]
	v_pk_mul_f32 v[36:37], v[46:47], v[40:41]
	v_pk_mul_f32 v[34:35], v[34:35], v[42:43]
	v_mul_f32_e32 v28, v28, v29
	v_mul_f32_e32 v29, v32, v33
	v_mul_f32_e32 v32, v36, v37
	v_mul_f32_e32 v33, v34, v35
	v_cvt_pk_bf16_f32 v44, v28, v29
	v_cvt_pk_bf16_f32 v45, v32, v33
	ds_read_b128 v[32:35], v137 offset:96
	v_cndmask_b32_e32 v31, v31, v62, vcc
	v_cndmask_b32_e32 v15, v30, v15, vcc
	v_lshlrev_b32_e32 v28, 16, v15
	v_lshlrev_b32_e32 v38, 16, v31
	v_and_b32_e32 v36, 0xffff0000, v15
	v_and_b32_e32 v40, 0xffff0000, v31
	v_mul_f32_e32 v15, 0xbfb8aa3b, v28
	v_mul_f32_e32 v31, 0xbfb8aa3b, v38
	v_mul_f32_e32 v30, 0xbfb8aa3b, v36
	v_mul_f32_e32 v42, 0xbfb8aa3b, v40
	v_exp_f32_e32 v15, v15
	v_exp_f32_e32 v31, v31
	v_exp_f32_e32 v30, v30
	v_exp_f32_e32 v42, v42
	v_add_f32_e32 v15, 1.0, v15
	v_add_f32_e32 v31, 1.0, v31
	v_add_f32_e32 v43, 1.0, v30
	v_add_f32_e32 v46, 1.0, v42
	v_rcp_f32_e32 v30, v15
	v_rcp_f32_e32 v42, v31
	v_mul_f32_e32 v29, v114, v14
	v_mul_f32_e32 v39, v112, v14
	v_mul_f32_e32 v37, v113, v14
	v_mul_f32_e32 v41, v78, v14
	s_waitcnt lgkmcnt(0)
; __device__ __forceinline__ unsigned pk2(float lo, float hi) { return pg8::cvt_pk_bf16(lo, hi); }
; __device__ __forceinline__ float siluf_(float v) { return v * __builtin_amdgcn_rcpf(1.f + __builtin_amdgcn_exp2f(-LOG2E * v)); }
; __device__ __forceinline__ void attn_unit(int b, int h, int qb, bf16_t* Q, const bf16_t* __restrict__ K, const bf16_t* __restrict__ Vt, const bf16_t* __restrict__ Z, const float* __restrict__ hg, float lam, ...
;     ...
;         for (int ip = 0; ip < 2; ++ip) { __builtin_amdgcn_sched_barrier(0);
;             u32x2 w[2];
;             const u32x4 zl = *(const u32x4*)(Z + offw + 32 * d + 16 * ip + 8 * hi_l);
;             const unsigned zsx = hi_l ? zl.x : zl.z, zsy = hi_l ? zl.y : zl.w;
;             const unsigned zrx = __shfl_xor(zsx, 32), zry = __shfl_xor(zsy, 32);
; #pragma unroll
;             for (int k = 0; k < 2; ++k) { const int i = 2 * ip + k, e = 32 * d + 8 * i;
;                 const f32x4 g4 = *(const f32x4*)(hg + e + 4 * hi_l);
;                 const u32x2 z2 = (k == 0) ? (hi_l ? (u32x2){zrx, zry} : (u32x2){zl.x, zl.y}) : (hi_l ? (u32x2){zl.z, zl.w} : (u32x2){zrx, zry});
;                 const float v0 = o[0][d][4 * i] * rs * g4[0] * siluf_(bflo(z2.x)), v1 = o[0][d][4 * i + 1] * rs * g4[1] * siluf_(bfhi(z2.x));
;                 const float v2 = o[0][d][4 * i + 2] * rs * g4[2] * siluf_(bflo(z2.y)), v3 = o[0][d][4 * i + 3] * rs * g4[3] * siluf_(bfhi(z2.y));
;                 w[k] = (u32x2){pk2(v0, v1), pk2(v2, v3)}; }
;             const u32x2 snd = hi_l ? w[0] : w[1];
;             const unsigned rx = __shfl_xor(snd.x, 32), ry = __shfl_xor(snd.y, 32);
;             const u32x4 st = hi_l ? (u32x4){rx, ry, w[1].x, w[1].y} : (u32x4){w[0].x, w[0].y, rx, ry};
;             *(u32x4*)(Q + offw + 32 * d + 16 * ip + 8 * hi_l) = st; }
	v_mov_b32_e32 v31, v32
	v_rcp_f32_e32 v32, v43
	v_mov_b32_e32 v43, v34
	v_rcp_f32_e32 v34, v46
	v_pk_mul_f32 v[28:29], v[30:31], v[28:29]
	v_pk_mul_f32 v[30:31], v[42:43], v[38:39]
	v_mul_f32_e32 v15, v28, v29
	v_mul_f32_e32 v38, v30, v31
	v_pk_mul_f32 v[28:29], v[32:33], v[36:37]
	v_pk_mul_f32 v[30:31], v[34:35], v[40:41]
	v_mul_f32_e32 v28, v28, v29
	v_mul_f32_e32 v29, v30, v31
	v_cvt_pk_bf16_f32 v15, v15, v28
	v_cvt_pk_bf16_f32 v29, v38, v29
	s_nop 0
	v_cndmask_b32_e32 v28, v44, v15, vcc
	v_cndmask_b32_e32 v30, v45, v29, vcc
	ds_bpermute_b32 v28, v217, v28
	ds_bpermute_b32 v32, v217, v30
	s_waitcnt lgkmcnt(1)
	v_cndmask_b32_e32 v30, v15, v28, vcc
	v_cndmask_b32_e32 v28, v28, v44, vcc
	s_waitcnt lgkmcnt(0)
	v_cndmask_b32_e32 v31, v29, v32, vcc
	v_cndmask_b32_e32 v29, v32, v45, vcc
	global_store_dwordx4 v[8:9], v[28:31], off offset:32
	s_nop 0
	ds_read_b128 v[32:35], v137 offset:128
	v_mul_f32_e32 v37, v77, v14
	v_mul_f32_e32 v39, v76, v14
	v_mul_f32_e32 v41, v75, v14
	v_mul_f32_e32 v43, v74, v14
	s_waitcnt vmcnt(7)
	v_mov_b32_e32 v28, v154
	v_mov_b32_e32 v29, v155
	v_mov_b32_e32 v30, v156
	v_mov_b32_e32 v31, v157
	v_cndmask_b32_e32 v15, v28, v30, vcc
	v_cndmask_b32_e32 v36, v29, v31, vcc
	ds_bpermute_b32 v62, v217, v36
	ds_bpermute_b32 v15, v217, v15
	s_waitcnt lgkmcnt(0)
	v_mov_b32_e32 v45, v32
	v_mov_b32_e32 v47, v34
	s_waitcnt lgkmcnt(1)
	v_cndmask_b32_e32 v29, v62, v29, vcc
	s_waitcnt lgkmcnt(0)
	v_cndmask_b32_e32 v28, v15, v28, vcc
	v_lshlrev_b32_e32 v36, 16, v28
	v_and_b32_e32 v38, 0xffff0000, v28
	v_lshlrev_b32_e32 v40, 16, v29
	v_and_b32_e32 v42, 0xffff0000, v29
	v_mul_f32_e32 v28, 0xbfb8aa3b, v36
	v_mul_f32_e32 v29, 0xbfb8aa3b, v38
	v_mul_f32_e32 v32, 0xbfb8aa3b, v40
	v_mul_f32_e32 v34, 0xbfb8aa3b, v42
	v_exp_f32_e32 v28, v28
	v_exp_f32_e32 v29, v29
	v_exp_f32_e32 v32, v32
	v_exp_f32_e32 v34, v34
	v_add_f32_e32 v28, 1.0, v28
	v_add_f32_e32 v29, 1.0, v29
	v_add_f32_e32 v46, 1.0, v32
	v_add_f32_e32 v34, 1.0, v34
	v_rcp_f32_e32 v44, v28
	v_rcp_f32_e32 v32, v29
	v_rcp_f32_e32 v46, v46
	v_rcp_f32_e32 v34, v34
	v_pk_mul_f32 v[28:29], v[44:45], v[36:37]
	v_pk_mul_f32 v[32:33], v[32:33], v[38:39]
	v_pk_mul_f32 v[36:37], v[46:47], v[40:41]
	v_pk_mul_f32 v[34:35], v[34:35], v[42:43]
	v_mul_f32_e32 v28, v28, v29
	v_mul_f32_e32 v29, v32, v33
	v_mul_f32_e32 v32, v36, v37
	v_mul_f32_e32 v33, v34, v35
	v_cvt_pk_bf16_f32 v44, v28, v29
	v_cvt_pk_bf16_f32 v45, v32, v33
	ds_read_b128 v[32:35], v137 offset:160
	v_cndmask_b32_e32 v31, v31, v62, vcc
	v_cndmask_b32_e32 v15, v30, v15, vcc
	v_lshlrev_b32_e32 v28, 16, v15
	v_lshlrev_b32_e32 v38, 16, v31
	v_and_b32_e32 v36, 0xffff0000, v15
	v_and_b32_e32 v40, 0xffff0000, v31
	v_mul_f32_e32 v15, 0xbfb8aa3b, v28
	v_mul_f32_e32 v31, 0xbfb8aa3b, v38
	v_mul_f32_e32 v30, 0xbfb8aa3b, v36
	v_mul_f32_e32 v42, 0xbfb8aa3b, v40
	v_exp_f32_e32 v15, v15
	v_exp_f32_e32 v31, v31
	v_exp_f32_e32 v30, v30
	v_exp_f32_e32 v42, v42
	v_add_f32_e32 v15, 1.0, v15
	v_add_f32_e32 v31, 1.0, v31
	v_add_f32_e32 v43, 1.0, v30
	v_add_f32_e32 v46, 1.0, v42
	v_rcp_f32_e32 v30, v15
	v_rcp_f32_e32 v42, v31
	v_mul_f32_e32 v29, v73, v14
	v_mul_f32_e32 v39, v71, v14
	v_mul_f32_e32 v37, v72, v14
	v_mul_f32_e32 v41, v70, v14
	s_waitcnt lgkmcnt(0)
	v_mov_b32_e32 v31, v32
	v_rcp_f32_e32 v32, v43
	v_mov_b32_e32 v43, v34
	v_rcp_f32_e32 v34, v46
	v_pk_mul_f32 v[28:29], v[30:31], v[28:29]
	v_pk_mul_f32 v[30:31], v[42:43], v[38:39]
	v_mul_f32_e32 v15, v28, v29
	v_mul_f32_e32 v38, v30, v31
	v_pk_mul_f32 v[28:29], v[32:33], v[36:37]
	v_pk_mul_f32 v[30:31], v[34:35], v[40:41]
	v_mul_f32_e32 v28, v28, v29
	v_mul_f32_e32 v29, v30, v31
	v_cvt_pk_bf16_f32 v15, v15, v28
	v_cvt_pk_bf16_f32 v29, v38, v29
	s_nop 0
	v_cndmask_b32_e32 v28, v44, v15, vcc
	v_cndmask_b32_e32 v30, v45, v29, vcc
	ds_bpermute_b32 v28, v217, v28
	ds_bpermute_b32 v32, v217, v30
	s_waitcnt lgkmcnt(1)
	v_cndmask_b32_e32 v30, v15, v28, vcc
	v_cndmask_b32_e32 v28, v28, v44, vcc
	s_waitcnt lgkmcnt(0)
	v_cndmask_b32_e32 v31, v29, v32, vcc
	v_cndmask_b32_e32 v29, v32, v45, vcc
	global_store_dwordx4 v[8:9], v[28:31], off offset:64
	s_nop 0
	ds_read_b128 v[32:35], v137 offset:192
	v_mul_f32_e32 v37, v69, v14
	v_mul_f32_e32 v39, v68, v14
	v_mul_f32_e32 v41, v67, v14
	v_mul_f32_e32 v43, v66, v14
	s_waitcnt vmcnt(7)
	v_mov_b32_e32 v28, v158
	v_mov_b32_e32 v29, v159
	v_mov_b32_e32 v30, v160
	v_mov_b32_e32 v31, v161
	v_cndmask_b32_e32 v15, v28, v30, vcc
	v_cndmask_b32_e32 v36, v29, v31, vcc
	ds_bpermute_b32 v62, v217, v36
	ds_bpermute_b32 v15, v217, v15
	s_waitcnt lgkmcnt(0)
	v_mov_b32_e32 v45, v32
	v_mov_b32_e32 v47, v34
	s_waitcnt lgkmcnt(1)
	v_cndmask_b32_e32 v29, v62, v29, vcc
	s_waitcnt lgkmcnt(0)
	v_cndmask_b32_e32 v28, v15, v28, vcc
	v_lshlrev_b32_e32 v36, 16, v28
	v_and_b32_e32 v38, 0xffff0000, v28
	v_lshlrev_b32_e32 v40, 16, v29
	v_and_b32_e32 v42, 0xffff0000, v29
	v_mul_f32_e32 v28, 0xbfb8aa3b, v36
	v_mul_f32_e32 v29, 0xbfb8aa3b, v38
	v_mul_f32_e32 v32, 0xbfb8aa3b, v40
	v_mul_f32_e32 v34, 0xbfb8aa3b, v42
	v_exp_f32_e32 v28, v28
	v_exp_f32_e32 v29, v29
	v_exp_f32_e32 v32, v32
	v_exp_f32_e32 v34, v34
	v_add_f32_e32 v28, 1.0, v28
	v_add_f32_e32 v29, 1.0, v29
	v_add_f32_e32 v46, 1.0, v32
	v_add_f32_e32 v34, 1.0, v34
	v_rcp_f32_e32 v44, v28
	v_rcp_f32_e32 v32, v29
	v_rcp_f32_e32 v46, v46
	v_rcp_f32_e32 v34, v34
	v_pk_mul_f32 v[28:29], v[44:45], v[36:37]
	v_pk_mul_f32 v[32:33], v[32:33], v[38:39]
	v_pk_mul_f32 v[36:37], v[46:47], v[40:41]
	v_pk_mul_f32 v[34:35], v[34:35], v[42:43]
	v_mul_f32_e32 v28, v28, v29
	v_mul_f32_e32 v29, v32, v33
	v_mul_f32_e32 v32, v36, v37
	v_mul_f32_e32 v33, v34, v35
	v_cvt_pk_bf16_f32 v44, v28, v29
	v_cvt_pk_bf16_f32 v45, v32, v33
	ds_read_b128 v[32:35], v137 offset:224
	v_cndmask_b32_e32 v31, v31, v62, vcc
	v_cndmask_b32_e32 v15, v30, v15, vcc
	v_lshlrev_b32_e32 v28, 16, v15
	v_lshlrev_b32_e32 v38, 16, v31
	v_and_b32_e32 v36, 0xffff0000, v15
	v_and_b32_e32 v40, 0xffff0000, v31
	v_mul_f32_e32 v15, 0xbfb8aa3b, v28
	v_mul_f32_e32 v31, 0xbfb8aa3b, v38
	v_mul_f32_e32 v30, 0xbfb8aa3b, v36
	v_mul_f32_e32 v42, 0xbfb8aa3b, v40
	v_exp_f32_e32 v15, v15
	v_exp_f32_e32 v31, v31
	v_exp_f32_e32 v30, v30
	v_exp_f32_e32 v42, v42
	v_add_f32_e32 v15, 1.0, v15
	v_add_f32_e32 v31, 1.0, v31
	v_add_f32_e32 v43, 1.0, v30
	v_add_f32_e32 v46, 1.0, v42
	v_rcp_f32_e32 v30, v15
	v_rcp_f32_e32 v42, v31
	v_mul_f32_e32 v29, v65, v14
	v_mul_f32_e32 v39, v61, v14
	v_mul_f32_e32 v37, v64, v14
	v_mul_f32_e32 v41, v60, v14
	s_waitcnt lgkmcnt(0)
; __device__ __forceinline__ unsigned pk2(float lo, float hi) { return pg8::cvt_pk_bf16(lo, hi); }
; __device__ __forceinline__ float siluf_(float v) { return v * __builtin_amdgcn_rcpf(1.f + __builtin_amdgcn_exp2f(-LOG2E * v)); }
; __device__ __forceinline__ void attn_unit(int b, int h, int qb, bf16_t* Q, const bf16_t* __restrict__ K, const bf16_t* __restrict__ Vt, const bf16_t* __restrict__ Z, const float* __restrict__ hg, float lam, ...
;     ...
;         for (int ip = 0; ip < 2; ++ip) { __builtin_amdgcn_sched_barrier(0);
;             u32x2 w[2];
;             const u32x4 zl = *(const u32x4*)(Z + offw + 32 * d + 16 * ip + 8 * hi_l);
;             const unsigned zsx = hi_l ? zl.x : zl.z, zsy = hi_l ? zl.y : zl.w;
;             const unsigned zrx = __shfl_xor(zsx, 32), zry = __shfl_xor(zsy, 32);
; #pragma unroll
;             for (int k = 0; k < 2; ++k) { const int i = 2 * ip + k, e = 32 * d + 8 * i;
;                 const f32x4 g4 = *(const f32x4*)(hg + e + 4 * hi_l);
;                 const u32x2 z2 = (k == 0) ? (hi_l ? (u32x2){zrx, zry} : (u32x2){zl.x, zl.y}) : (hi_l ? (u32x2){zl.z, zl.w} : (u32x2){zrx, zry});
;                 const float v0 = o[0][d][4 * i] * rs * g4[0] * siluf_(bflo(z2.x)), v1 = o[0][d][4 * i + 1] * rs * g4[1] * siluf_(bfhi(z2.x));
;                 const float v2 = o[0][d][4 * i + 2] * rs * g4[2] * siluf_(bflo(z2.y)), v3 = o[0][d][4 * i + 3] * rs * g4[3] * siluf_(bfhi(z2.y));
;                 w[k] = (u32x2){pk2(v0, v1), pk2(v2, v3)}; }
;             const u32x2 snd = hi_l ? w[0] : w[1];
;             const unsigned rx = __shfl_xor(snd.x, 32), ry = __shfl_xor(snd.y, 32);
;             const u32x4 st = hi_l ? (u32x4){rx, ry, w[1].x, w[1].y} : (u32x4){w[0].x, w[0].y, rx, ry};
;             *(u32x4*)(Q + offw + 32 * d + 16 * ip + 8 * hi_l) = st; }
	v_mov_b32_e32 v31, v32
	v_rcp_f32_e32 v32, v43
	v_mov_b32_e32 v43, v34
	v_rcp_f32_e32 v34, v46
	v_pk_mul_f32 v[28:29], v[30:31], v[28:29]
	v_pk_mul_f32 v[30:31], v[42:43], v[38:39]
	v_mul_f32_e32 v15, v28, v29
	v_mul_f32_e32 v38, v30, v31
	v_pk_mul_f32 v[28:29], v[32:33], v[36:37]
	v_pk_mul_f32 v[30:31], v[34:35], v[40:41]
	v_mul_f32_e32 v28, v28, v29
	v_mul_f32_e32 v29, v30, v31
	v_cvt_pk_bf16_f32 v15, v15, v28
	v_cvt_pk_bf16_f32 v29, v38, v29
	s_nop 0
	v_cndmask_b32_e32 v28, v44, v15, vcc
	v_cndmask_b32_e32 v30, v45, v29, vcc
	ds_bpermute_b32 v28, v217, v28
	ds_bpermute_b32 v32, v217, v30
	s_waitcnt lgkmcnt(1)
	v_cndmask_b32_e32 v30, v15, v28, vcc
	v_cndmask_b32_e32 v28, v28, v44, vcc
	s_waitcnt lgkmcnt(0)
	v_cndmask_b32_e32 v31, v29, v32, vcc
	v_cndmask_b32_e32 v29, v32, v45, vcc
	global_store_dwordx4 v[8:9], v[28:31], off offset:96
	s_nop 0
	ds_read_b128 v[32:35], v137 offset:256
	v_mul_f32_e32 v41, v57, v14
	v_mul_f32_e32 v37, v59, v14
	v_mul_f32_e32 v39, v58, v14
	v_mul_f32_e32 v43, v56, v14
	s_waitcnt vmcnt(7)
	v_mov_b32_e32 v28, v162
	v_mov_b32_e32 v29, v163
	v_mov_b32_e32 v30, v164
	v_mov_b32_e32 v31, v165
	v_cndmask_b32_e32 v15, v28, v30, vcc
	v_cndmask_b32_e32 v36, v29, v31, vcc
	ds_bpermute_b32 v57, v217, v36
	ds_bpermute_b32 v15, v217, v15
	s_waitcnt lgkmcnt(0)
	v_mov_b32_e32 v45, v32
	v_mov_b32_e32 v47, v34
	s_waitcnt lgkmcnt(1)
	v_cndmask_b32_e32 v29, v57, v29, vcc
	s_waitcnt lgkmcnt(0)
	v_cndmask_b32_e32 v28, v15, v28, vcc
	v_lshlrev_b32_e32 v36, 16, v28
	v_and_b32_e32 v38, 0xffff0000, v28
	v_lshlrev_b32_e32 v40, 16, v29
	v_and_b32_e32 v42, 0xffff0000, v29
	v_mul_f32_e32 v28, 0xbfb8aa3b, v36
	v_mul_f32_e32 v29, 0xbfb8aa3b, v38
	v_mul_f32_e32 v32, 0xbfb8aa3b, v40
	v_mul_f32_e32 v34, 0xbfb8aa3b, v42
	v_exp_f32_e32 v28, v28
	v_exp_f32_e32 v29, v29
	v_exp_f32_e32 v32, v32
	v_exp_f32_e32 v34, v34
	v_add_f32_e32 v28, 1.0, v28
	v_add_f32_e32 v29, 1.0, v29
	v_add_f32_e32 v46, 1.0, v32
	v_add_f32_e32 v34, 1.0, v34
	v_rcp_f32_e32 v44, v28
	v_rcp_f32_e32 v32, v29
	v_rcp_f32_e32 v46, v46
	v_rcp_f32_e32 v34, v34
	v_pk_mul_f32 v[28:29], v[44:45], v[36:37]
	v_pk_mul_f32 v[32:33], v[32:33], v[38:39]
	v_pk_mul_f32 v[36:37], v[46:47], v[40:41]
	v_pk_mul_f32 v[34:35], v[34:35], v[42:43]
	v_mul_f32_e32 v28, v28, v29
	v_mul_f32_e32 v29, v32, v33
	v_mul_f32_e32 v32, v36, v37
	v_mul_f32_e32 v33, v34, v35
	v_cvt_pk_bf16_f32 v44, v28, v29
	v_cvt_pk_bf16_f32 v45, v32, v33
	ds_read_b128 v[32:35], v137 offset:288
	v_cndmask_b32_e32 v31, v31, v57, vcc
	v_cndmask_b32_e32 v15, v30, v15, vcc
	v_lshlrev_b32_e32 v28, 16, v15
	v_lshlrev_b32_e32 v38, 16, v31
	v_and_b32_e32 v36, 0xffff0000, v15
	v_and_b32_e32 v40, 0xffff0000, v31
	v_mul_f32_e32 v15, 0xbfb8aa3b, v28
	v_mul_f32_e32 v31, 0xbfb8aa3b, v38
	v_mul_f32_e32 v30, 0xbfb8aa3b, v36
	v_mul_f32_e32 v42, 0xbfb8aa3b, v40
	v_exp_f32_e32 v15, v15
	v_exp_f32_e32 v31, v31
	v_exp_f32_e32 v30, v30
	v_exp_f32_e32 v42, v42
	v_add_f32_e32 v15, 1.0, v15
	v_add_f32_e32 v31, 1.0, v31
	v_add_f32_e32 v43, 1.0, v30
	v_add_f32_e32 v46, 1.0, v42
	v_rcp_f32_e32 v30, v15
	v_rcp_f32_e32 v42, v31
	v_mul_f32_e32 v29, v55, v14
	v_mul_f32_e32 v39, v53, v14
	v_mul_f32_e32 v37, v54, v14
	v_mul_f32_e32 v41, v52, v14
	s_waitcnt lgkmcnt(0)
	v_mov_b32_e32 v31, v32
	v_rcp_f32_e32 v32, v43
	v_mov_b32_e32 v43, v34
	v_rcp_f32_e32 v34, v46
	v_pk_mul_f32 v[28:29], v[30:31], v[28:29]
	v_pk_mul_f32 v[30:31], v[42:43], v[38:39]
	v_mul_f32_e32 v15, v28, v29
	v_mul_f32_e32 v38, v30, v31
	v_pk_mul_f32 v[28:29], v[32:33], v[36:37]
	v_pk_mul_f32 v[30:31], v[34:35], v[40:41]
	v_mul_f32_e32 v28, v28, v29
	v_mul_f32_e32 v29, v30, v31
	v_cvt_pk_bf16_f32 v15, v15, v28
	v_cvt_pk_bf16_f32 v29, v38, v29
	s_nop 0
	v_cndmask_b32_e32 v28, v44, v15, vcc
	v_cndmask_b32_e32 v30, v45, v29, vcc
	ds_bpermute_b32 v28, v217, v28
	ds_bpermute_b32 v32, v217, v30
	s_waitcnt lgkmcnt(1)
	v_cndmask_b32_e32 v30, v15, v28, vcc
	v_cndmask_b32_e32 v28, v28, v44, vcc
	s_waitcnt lgkmcnt(0)
	v_cndmask_b32_e32 v31, v29, v32, vcc
	v_cndmask_b32_e32 v29, v32, v45, vcc
	global_store_dwordx4 v[8:9], v[28:31], off offset:128
	s_nop 0
	ds_read_b128 v[32:35], v137 offset:320
	v_mul_f32_e32 v42, v48, v14
	v_mul_f32_e32 v40, v49, v14
	v_mul_f32_e32 v36, v51, v14
	v_mul_f32_e32 v38, v50, v14
	v_mul_f32_e32 v26, v26, v14
	v_mul_f32_e32 v24, v24, v14
	s_waitcnt vmcnt(7)
	v_mov_b32_e32 v28, v166
	v_mov_b32_e32 v29, v167
	v_mov_b32_e32 v30, v168
	v_mov_b32_e32 v31, v169
	v_cndmask_b32_e32 v15, v28, v30, vcc
	v_cndmask_b32_e32 v37, v29, v31, vcc
	ds_bpermute_b32 v48, v217, v37
	ds_bpermute_b32 v15, v217, v15
	s_waitcnt lgkmcnt(0)
	v_mov_b32_e32 v44, v33
	v_mov_b32_e32 v46, v35
	s_waitcnt lgkmcnt(1)
	v_cndmask_b32_e32 v29, v48, v29, vcc
	s_waitcnt lgkmcnt(0)
	v_cndmask_b32_e32 v28, v15, v28, vcc
	v_lshlrev_b32_e32 v37, 16, v28
	v_and_b32_e32 v39, 0xffff0000, v28
	v_lshlrev_b32_e32 v41, 16, v29
	v_and_b32_e32 v43, 0xffff0000, v29
	v_mul_f32_e32 v28, 0xbfb8aa3b, v37
	v_mul_f32_e32 v29, 0xbfb8aa3b, v39
	v_mul_f32_e32 v33, 0xbfb8aa3b, v41
	v_mul_f32_e32 v35, 0xbfb8aa3b, v43
	v_exp_f32_e32 v28, v28
	v_exp_f32_e32 v29, v29
	v_exp_f32_e32 v33, v33
	v_exp_f32_e32 v35, v35
	v_add_f32_e32 v28, 1.0, v28
	v_add_f32_e32 v29, 1.0, v29
	v_add_f32_e32 v47, 1.0, v33
	v_add_f32_e32 v49, 1.0, v35
	v_rcp_f32_e32 v33, v28
	v_rcp_f32_e32 v45, v29
	v_rcp_f32_e32 v35, v47
	v_rcp_f32_e32 v47, v49
	v_pk_mul_f32 v[28:29], v[32:33], v[36:37]
	v_pk_mul_f32 v[32:33], v[44:45], v[38:39]
	v_pk_mul_f32 v[34:35], v[34:35], v[40:41]
	v_pk_mul_f32 v[36:37], v[46:47], v[42:43]
	v_mul_f32_e32 v28, v28, v29
	v_mul_f32_e32 v29, v32, v33
	v_mul_f32_e32 v32, v34, v35
	v_mul_f32_e32 v33, v36, v37
	v_cvt_pk_bf16_f32 v44, v28, v29
	v_cvt_pk_bf16_f32 v45, v32, v33
	ds_read_b128 v[32:35], v137 offset:352
	v_mul_f32_e32 v36, v25, v14
	v_cndmask_b32_e32 v25, v31, v48, vcc
	v_cndmask_b32_e32 v15, v30, v15, vcc
	v_mul_f32_e32 v28, v27, v14
	v_lshlrev_b32_e32 v29, 16, v15
	v_and_b32_e32 v27, 0xffff0000, v15
	v_lshlrev_b32_e32 v37, 16, v25
	v_and_b32_e32 v25, 0xffff0000, v25
	v_mul_f32_e32 v15, 0xbfb8aa3b, v29
	v_mul_f32_e32 v30, 0xbfb8aa3b, v27
	v_mul_f32_e32 v38, 0xbfb8aa3b, v25
	v_mul_f32_e32 v31, 0xbfb8aa3b, v37
	v_exp_f32_e32 v15, v15
	v_exp_f32_e32 v30, v30
	v_exp_f32_e32 v38, v38
	v_exp_f32_e32 v31, v31
	v_add_f32_e32 v15, 1.0, v15
	v_add_f32_e32 v30, 1.0, v30
	v_add_f32_e32 v38, 1.0, v38
	v_add_f32_e32 v40, 1.0, v31
	v_rcp_f32_e32 v31, v15
	v_rcp_f32_e32 v39, v30
	v_rcp_f32_e32 v43, v38
	v_rcp_f32_e32 v41, v40
	s_waitcnt lgkmcnt(0)
; __device__ __forceinline__ unsigned pk2(float lo, float hi) { return pg8::cvt_pk_bf16(lo, hi); }
; __device__ __forceinline__ float siluf_(float v) { return v * __builtin_amdgcn_rcpf(1.f + __builtin_amdgcn_exp2f(-LOG2E * v)); }
; __device__ __forceinline__ void attn_unit(int b, int h, int qb, bf16_t* Q, const bf16_t* __restrict__ K, const bf16_t* __restrict__ Vt, const bf16_t* __restrict__ Z, const float* __restrict__ hg, float lam, ...
;     ...
;         for (int ip = 0; ip < 2; ++ip) { __builtin_amdgcn_sched_barrier(0);
;             u32x2 w[2];
;             const u32x4 zl = *(const u32x4*)(Z + offw + 32 * d + 16 * ip + 8 * hi_l);
;             const unsigned zsx = hi_l ? zl.x : zl.z, zsy = hi_l ? zl.y : zl.w;
;             const unsigned zrx = __shfl_xor(zsx, 32), zry = __shfl_xor(zsy, 32);
; #pragma unroll
;             for (int k = 0; k < 2; ++k) { const int i = 2 * ip + k, e = 32 * d + 8 * i;
;                 const f32x4 g4 = *(const f32x4*)(hg + e + 4 * hi_l);
;                 const u32x2 z2 = (k == 0) ? (hi_l ? (u32x2){zrx, zry} : (u32x2){zl.x, zl.y}) : (hi_l ? (u32x2){zl.z, zl.w} : (u32x2){zrx, zry});
;                 const float v0 = o[0][d][4 * i] * rs * g4[0] * siluf_(bflo(z2.x)), v1 = o[0][d][4 * i + 1] * rs * g4[1] * siluf_(bfhi(z2.x));
;                 const float v2 = o[0][d][4 * i + 2] * rs * g4[2] * siluf_(bflo(z2.y)), v3 = o[0][d][4 * i + 3] * rs * g4[3] * siluf_(bfhi(z2.y));
;                 w[k] = (u32x2){pk2(v0, v1), pk2(v2, v3)}; }
;             const u32x2 snd = hi_l ? w[0] : w[1];
;             const unsigned rx = __shfl_xor(snd.x, 32), ry = __shfl_xor(snd.y, 32);
;             const u32x4 st = hi_l ? (u32x4){rx, ry, w[1].x, w[1].y} : (u32x4){w[0].x, w[0].y, rx, ry};
;             *(u32x4*)(Q + offw + 32 * d + 16 * ip + 8 * hi_l) = st; }
	v_mov_b32_e32 v30, v32
	v_mov_b32_e32 v38, v33
	v_mov_b32_e32 v42, v35
	v_mov_b32_e32 v40, v34
	v_pk_mul_f32 v[28:29], v[30:31], v[28:29]
	v_pk_mul_f32 v[26:27], v[38:39], v[26:27]
	v_pk_mul_f32 v[24:25], v[42:43], v[24:25]
	v_pk_mul_f32 v[30:31], v[40:41], v[36:37]
	v_mul_f32_e32 v15, v28, v29
	v_mul_f32_e32 v26, v26, v27
	v_mul_f32_e32 v24, v24, v25
	v_mul_f32_e32 v27, v30, v31
	v_cvt_pk_bf16_f32 v15, v15, v26
	v_cvt_pk_bf16_f32 v25, v27, v24
	s_nop 0
	v_cndmask_b32_e32 v24, v44, v15, vcc
	v_cndmask_b32_e32 v26, v45, v25, vcc
	ds_bpermute_b32 v24, v217, v24
	ds_bpermute_b32 v28, v217, v26
	s_waitcnt lgkmcnt(1)
	v_cndmask_b32_e32 v26, v15, v24, vcc
	v_cndmask_b32_e32 v24, v24, v44, vcc
	s_waitcnt lgkmcnt(0)
	v_cndmask_b32_e32 v27, v25, v28, vcc
	v_cndmask_b32_e32 v25, v28, v45, vcc
	global_store_dwordx4 v[8:9], v[24:27], off offset:160
	s_nop 0
	ds_read_b128 v[28:31], v137 offset:384
	v_mul_f32_e32 v34, v21, v14
	v_mul_f32_e32 v32, v23, v14
	v_mul_f32_e32 v22, v22, v14
	v_mul_f32_e32 v20, v20, v14
	v_mul_f32_e32 v18, v18, v14
	v_mul_f32_e32 v16, v16, v14
	s_waitcnt vmcnt(7)
	v_mov_b32_e32 v24, v170
	v_mov_b32_e32 v25, v171
	v_mov_b32_e32 v26, v172
	v_mov_b32_e32 v27, v173
	v_cndmask_b32_e32 v15, v24, v26, vcc
	v_cndmask_b32_e32 v21, v25, v27, vcc
	ds_bpermute_b32 v40, v217, v21
	ds_bpermute_b32 v15, v217, v15
	s_waitcnt lgkmcnt(0)
	v_mov_b32_e32 v36, v29
	v_mov_b32_e32 v38, v31
	s_waitcnt lgkmcnt(1)
	v_cndmask_b32_e32 v21, v40, v25, vcc
	s_waitcnt lgkmcnt(0)
	v_cndmask_b32_e32 v23, v15, v24, vcc
	v_lshlrev_b32_e32 v29, 16, v23
	v_and_b32_e32 v37, 0xffff0000, v23
	v_lshlrev_b32_e32 v31, 16, v21
	v_and_b32_e32 v39, 0xffff0000, v21
	v_mul_f32_e32 v21, 0xbfb8aa3b, v29
	v_mul_f32_e32 v23, 0xbfb8aa3b, v37
	v_mul_f32_e32 v24, 0xbfb8aa3b, v31
	v_mul_f32_e32 v25, 0xbfb8aa3b, v39
	v_exp_f32_e32 v21, v21
	v_exp_f32_e32 v23, v23
	v_exp_f32_e32 v24, v24
	v_exp_f32_e32 v25, v25
	v_add_f32_e32 v21, 1.0, v21
	v_add_f32_e32 v23, 1.0, v23
	v_add_f32_e32 v24, 1.0, v24
	v_add_f32_e32 v25, 1.0, v25
	v_rcp_f32_e32 v33, v21
	v_rcp_f32_e32 v23, v23
	v_rcp_f32_e32 v35, v24
	v_rcp_f32_e32 v21, v25
	v_pk_mul_f32 v[24:25], v[32:33], v[28:29]
	v_pk_mul_f32 v[22:23], v[22:23], v[36:37]
	v_pk_mul_f32 v[28:29], v[34:35], v[30:31]
	v_pk_mul_f32 v[20:21], v[20:21], v[38:39]
	v_mul_f32_e32 v22, v22, v23
	v_mul_f32_e32 v23, v28, v29
	v_mul_f32_e32 v20, v20, v21
	v_mul_f32_e32 v24, v24, v25
	v_cvt_pk_bf16_f32 v36, v24, v22
	v_cvt_pk_bf16_f32 v37, v23, v20
	ds_read_b128 v[20:23], v137 offset:416
	v_mul_f32_e32 v28, v17, v14
	v_cndmask_b32_e32 v17, v27, v40, vcc
	v_cndmask_b32_e32 v15, v26, v15, vcc
	v_lshlrev_b32_e32 v27, 16, v15
	v_and_b32_e32 v31, 0xffff0000, v15
	v_and_b32_e32 v35, 0xffff0000, v17
	v_lshlrev_b32_e32 v33, 16, v17
	v_mul_f32_e32 v15, 0xbfb8aa3b, v27
	v_mul_f32_e32 v17, 0xbfb8aa3b, v31
	v_mul_f32_e32 v25, 0xbfb8aa3b, v35
	v_mul_f32_e32 v24, v19, v14
	v_mul_f32_e32 v19, 0xbfb8aa3b, v33
	v_exp_f32_e32 v15, v15
	v_exp_f32_e32 v17, v17
	v_exp_f32_e32 v25, v25
	v_exp_f32_e32 v19, v19
	v_add_f32_e32 v15, 1.0, v15
	v_add_f32_e32 v17, 1.0, v17
	v_add_f32_e32 v30, 1.0, v25
	v_add_f32_e32 v26, 1.0, v19
	v_rcp_f32_e32 v25, v15
	v_rcp_f32_e32 v19, v17
	v_rcp_f32_e32 v17, v30
	v_rcp_f32_e32 v29, v26
	s_waitcnt lgkmcnt(0)
	v_mov_b32_e32 v26, v20
	v_mov_b32_e32 v30, v21
	v_mov_b32_e32 v34, v23
	v_mov_b32_e32 v32, v22
	v_pk_mul_f32 v[20:21], v[24:25], v[26:27]
	v_pk_mul_f32 v[18:19], v[18:19], v[30:31]
	v_pk_mul_f32 v[16:17], v[16:17], v[34:35]
	v_pk_mul_f32 v[22:23], v[28:29], v[32:33]
	v_mul_f32_e32 v15, v20, v21
	v_mul_f32_e32 v18, v18, v19
	v_mul_f32_e32 v16, v16, v17
	v_mul_f32_e32 v19, v22, v23
	v_cvt_pk_bf16_f32 v15, v15, v18
	v_cvt_pk_bf16_f32 v17, v19, v16
	s_nop 0
	v_cndmask_b32_e32 v16, v36, v15, vcc
	v_cndmask_b32_e32 v18, v37, v17, vcc
	ds_bpermute_b32 v16, v217, v16
	ds_bpermute_b32 v20, v217, v18
	s_waitcnt lgkmcnt(1)
; __device__ __forceinline__ unsigned pk2(float lo, float hi) { return pg8::cvt_pk_bf16(lo, hi); }
; __device__ __forceinline__ float siluf_(float v) { return v * __builtin_amdgcn_rcpf(1.f + __builtin_amdgcn_exp2f(-LOG2E * v)); }
; __device__ __forceinline__ void attn_unit(int b, int h, int qb, bf16_t* Q, const bf16_t* __restrict__ K, const bf16_t* __restrict__ Vt, const bf16_t* __restrict__ Z, const float* __restrict__ hg, float lam, ...
;     ...
;         for (int ip = 0; ip < 2; ++ip) { __builtin_amdgcn_sched_barrier(0);
;             u32x2 w[2];
;             const u32x4 zl = *(const u32x4*)(Z + offw + 32 * d + 16 * ip + 8 * hi_l);
;             const unsigned zsx = hi_l ? zl.x : zl.z, zsy = hi_l ? zl.y : zl.w;
;             const unsigned zrx = __shfl_xor(zsx, 32), zry = __shfl_xor(zsy, 32);
; #pragma unroll
;             for (int k = 0; k < 2; ++k) { const int i = 2 * ip + k, e = 32 * d + 8 * i;
;                 const f32x4 g4 = *(const f32x4*)(hg + e + 4 * hi_l);
;                 const u32x2 z2 = (k == 0) ? (hi_l ? (u32x2){zrx, zry} : (u32x2){zl.x, zl.y}) : (hi_l ? (u32x2){zl.z, zl.w} : (u32x2){zrx, zry});
;                 const float v0 = o[0][d][4 * i] * rs * g4[0] * siluf_(bflo(z2.x)), v1 = o[0][d][4 * i + 1] * rs * g4[1] * siluf_(bfhi(z2.x));
;                 const float v2 = o[0][d][4 * i + 2] * rs * g4[2] * siluf_(bflo(z2.y)), v3 = o[0][d][4 * i + 3] * rs * g4[3] * siluf_(bfhi(z2.y));
;                 w[k] = (u32x2){pk2(v0, v1), pk2(v2, v3)}; }
;             const u32x2 snd = hi_l ? w[0] : w[1];
;             const unsigned rx = __shfl_xor(snd.x, 32), ry = __shfl_xor(snd.y, 32);
;             const u32x4 st = hi_l ? (u32x4){rx, ry, w[1].x, w[1].y} : (u32x4){w[0].x, w[0].y, rx, ry};
;             *(u32x4*)(Q + offw + 32 * d + 16 * ip + 8 * hi_l) = st; }
	v_cndmask_b32_e32 v18, v15, v16, vcc
	v_cndmask_b32_e32 v16, v16, v36, vcc
	s_waitcnt lgkmcnt(0)
	v_cndmask_b32_e32 v19, v17, v20, vcc
	v_cndmask_b32_e32 v17, v20, v37, vcc
	global_store_dwordx4 v[8:9], v[16:19], off offset:192
	s_nop 0
	ds_read_b128 v[20:23], v137 offset:448
	v_mul_f32_e32 v12, v7, v14
	v_mul_f32_e32 v24, v5, v14
	v_mul_f32_e32 v6, v6, v14
	v_mul_f32_e32 v4, v4, v14
	v_mul_f32_e32 v2, v2, v14
	v_mul_f32_e32 v0, v0, v14
	s_mov_b64 s[8:9], 0
	s_waitcnt vmcnt(7)
	v_mov_b32_e32 v16, v174
	v_mov_b32_e32 v17, v175
	v_mov_b32_e32 v18, v176
	v_mov_b32_e32 v19, v177
	v_cndmask_b32_e32 v5, v16, v18, vcc
	v_cndmask_b32_e32 v7, v17, v19, vcc
	ds_bpermute_b32 v15, v217, v7
	ds_bpermute_b32 v30, v217, v5
	s_waitcnt lgkmcnt(0)
	v_mov_b32_e32 v26, v21
	v_mov_b32_e32 v28, v23
	s_waitcnt lgkmcnt(1)
	v_cndmask_b32_e32 v5, v15, v17, vcc
	s_waitcnt lgkmcnt(0)
	v_cndmask_b32_e32 v7, v30, v16, vcc
	v_lshlrev_b32_e32 v21, 16, v7
	v_and_b32_e32 v27, 0xffff0000, v7
	v_lshlrev_b32_e32 v23, 16, v5
	v_and_b32_e32 v29, 0xffff0000, v5
	v_mul_f32_e32 v5, 0xbfb8aa3b, v21
	v_mul_f32_e32 v7, 0xbfb8aa3b, v27
	v_mul_f32_e32 v13, 0xbfb8aa3b, v23
	v_mul_f32_e32 v16, 0xbfb8aa3b, v29
	v_exp_f32_e32 v5, v5
	v_exp_f32_e32 v7, v7
	v_exp_f32_e32 v13, v13
	v_exp_f32_e32 v16, v16
	v_add_f32_e32 v5, 1.0, v5
	v_add_f32_e32 v7, 1.0, v7
	v_add_f32_e32 v17, 1.0, v13
	v_add_f32_e32 v16, 1.0, v16
	v_rcp_f32_e32 v13, v5
	v_rcp_f32_e32 v7, v7
	v_rcp_f32_e32 v25, v17
	v_rcp_f32_e32 v5, v16
	v_pk_mul_f32 v[12:13], v[12:13], v[20:21]
	v_pk_mul_f32 v[6:7], v[6:7], v[26:27]
	v_pk_mul_f32 v[16:17], v[24:25], v[22:23]
	v_pk_mul_f32 v[4:5], v[4:5], v[28:29]
	v_mul_f32_e32 v6, v6, v7
	v_mul_f32_e32 v7, v16, v17
	v_mul_f32_e32 v4, v4, v5
	v_mul_f32_e32 v12, v12, v13
	v_cvt_pk_bf16_f32 v22, v12, v6
	v_cvt_pk_bf16_f32 v23, v7, v4
	ds_read_b128 v[4:7], v137 offset:480
	v_mul_f32_e32 v10, v3, v14
	v_mul_f32_e32 v12, v1, v14
	v_cndmask_b32_e32 v1, v19, v15, vcc
	v_cndmask_b32_e32 v3, v18, v30, vcc
	v_lshlrev_b32_e32 v15, 16, v3
	v_and_b32_e32 v17, 0xffff0000, v3
	v_lshlrev_b32_e32 v19, 16, v1
	v_and_b32_e32 v21, 0xffff0000, v1
	v_mul_f32_e32 v1, 0xbfb8aa3b, v15
	v_mul_f32_e32 v3, 0xbfb8aa3b, v17
	v_mul_f32_e32 v11, 0xbfb8aa3b, v19
	v_mul_f32_e32 v13, 0xbfb8aa3b, v21
	v_exp_f32_e32 v1, v1
	v_exp_f32_e32 v3, v3
	v_exp_f32_e32 v11, v11
	v_exp_f32_e32 v13, v13
	v_add_f32_e32 v1, 1.0, v1
	v_add_f32_e32 v14, 1.0, v3
	v_add_f32_e32 v16, 1.0, v11
	v_add_f32_e32 v13, 1.0, v13
	v_rcp_f32_e32 v3, v1
	v_rcp_f32_e32 v11, v14
	v_rcp_f32_e32 v1, v16
	v_rcp_f32_e32 v13, v13
	s_waitcnt lgkmcnt(0)
	v_mov_b32_e32 v14, v4
	v_mov_b32_e32 v16, v5
	v_mov_b32_e32 v18, v6
	v_mov_b32_e32 v20, v7
	v_pk_mul_f32 v[2:3], v[2:3], v[14:15]
	v_pk_mul_f32 v[4:5], v[10:11], v[16:17]
	v_pk_mul_f32 v[0:1], v[0:1], v[18:19]
	v_pk_mul_f32 v[6:7], v[12:13], v[20:21]
	v_mul_f32_e32 v2, v2, v3
	v_mul_f32_e32 v3, v4, v5
	v_mul_f32_e32 v0, v0, v1
	v_mul_f32_e32 v1, v6, v7
	v_cvt_pk_bf16_f32 v2, v2, v3
	v_cvt_pk_bf16_f32 v1, v0, v1
	s_nop 0
	v_cndmask_b32_e32 v0, v22, v2, vcc
	v_cndmask_b32_e32 v3, v23, v1, vcc
	ds_bpermute_b32 v0, v217, v0
	ds_bpermute_b32 v4, v217, v3
	s_waitcnt lgkmcnt(1)
	v_cndmask_b32_e32 v2, v2, v0, vcc
	v_cndmask_b32_e32 v0, v0, v22, vcc
	s_waitcnt lgkmcnt(0)
	v_cndmask_b32_e32 v3, v1, v4, vcc
	v_cndmask_b32_e32 v1, v4, v23, vcc
	global_store_dwordx4 v[8:9], v[0:3], off offset:224

; #define AT_LOADK(tt) do { const unsigned ko = kgo + (unsigned)(tt) * (64 * BR * 2); ks0 = *(const u32x4*)((const char*)K + ko); ks1 = *(const u32x4*)((const char*)K + ko + 32 * BR * 2); } while (0)
; #define AT_LOADV(tt) do { const unsigned vo = vgo + (unsigned)(tt) * 128; vs0 = *(const u32x4*)((const char*)Vt + vo); vs1 = *(const u32x4*)((const char*)Vt + vo + 64 * SEQ * 2); } while (0)
; __device__ __forceinline__ void attn_unit(int b, int h, int qb, bf16_t* Q, const bf16_t* __restrict__ K, const bf16_t* __restrict__ Vt, const bf16_t* __restrict__ Z, const float* __restrict__ hg, float lam, ...
;     ...
;     const float slope2 = __builtin_bit_cast(float, __builtin_amdgcn_readfirstlane(__builtin_bit_cast(int, tab[h])));
;     bf16x8 qf[2][4];
;     { const bf16_t* qp = Q + (rowbase + qw0 + r32) * BR + h * 128 + 8 * hi;
; #pragma unroll
;       for (int sub = 0; sub < 2; ++sub)
; #pragma unroll
;           for (int d0 = 0; d0 < 4; ++d0) qf[sub][d0] = *(const bf16x8*)(qp + sub * 64 + d0 * 16); }
;     const unsigned kgo = (unsigned)(((rowbase + (tid >> 4)) * BR + h * 128 + (tid & 15) * 8) * 2);
;     const int kl = (tid >> 4) * KROW + (tid & 15) * 16;
;     const unsigned vgo = (unsigned)((((size_t)b * BR + h * 128 + (tid >> 3)) * SEQ + (tid & 7) * 8) * 2);
;     const int vl = AT_VOFF + (tid >> 3) * VROW + (tid & 7) * 16;
;     const int NT = 4 * (qb + 1), last_w = (qw0 + 31) >> 6;
;     int tlo_w = 0; if (Dwin < 4096.f) { const int kmin_w = qw0 - (int)Dwin - 1; tlo_w = kmin_w > 0 ? (kmin_w >> 6) : 0; }
;     f32x16 o[2][4];
; #pragma unroll
;     for (int s = 0; s < 2; ++s)
; #pragma unroll
;         for (int d = 0; d < 4; ++d)
; #pragma unroll
;             for (int r = 0; r < 16; ++r) o[s][d][r] = 0.f;
;     float lsum[2] = {0.f, 0.f};
;     u32x4 ks0, ks1, vs0, vs1;
;     ...
;     AT_LOADK(tfirst); AT_LOADV(tfirst); AT_WRITEK(tfirst & 1); AT_WRITEV(tfirst & 1);
;     __syncthreads();
; __device__ __forceinline__ void attn_phase(const Params& P, LAS unsigned char* lds, int bx, int tid_in) {
;     ...
;         const int h = 15 - (u >> 4), qb = 15 - (u & 15);
;         const float Df = tab[16 + h];
;         int tfirst = 0;
;         if (Df < 4096.f) { const int kmin = qb * 256 - (int)Df - 1; tfirst = kmin > 0 ? (kmin >> 6) : 0; }
;         tfirst = __builtin_amdgcn_readfirstlane(tfirst);
.LBB0_243:
	s_or_b64 exec, exec, s[8:9]
	s_ashr_i32 s10, s11, 4
	s_sub_i32 s18, 31, s10
	s_sub_i32 s8, 15, s10
	s_andn2_b32 s11, 15, s11
	s_lshl_b64 s[62:63], s[18:19], 2
	s_add_u32 s62, s73, s62
	s_addc_u32 s63, s74, s63
	global_load_dword v0, v211, s[62:63]
	s_lshl_b32 s62, s11, 8
	s_mov_b32 s9, s19
	v_mov_b32_e32 v223, v211
	v_mov_b32_e32 v225, 0
	v_mov_b32_e32 v224, v225
	v_mov_b32_e32 v79, v225
	v_mov_b32_e32 v78, v225
	v_mov_b32_e32 v77, v225
	v_mov_b32_e32 v76, v225
	v_mov_b32_e32 v75, v225
	v_mov_b32_e32 v74, v225
	v_mov_b32_e32 v73, v225
	v_mov_b32_e32 v72, v225
	v_mov_b32_e32 v71, v225
	v_mov_b32_e32 v70, v225
	v_mov_b32_e32 v69, v225
	v_mov_b32_e32 v68, v225
	v_mov_b32_e32 v67, v225
	v_mov_b32_e32 v66, v225
	v_mov_b32_e32 v65, v225
	v_mov_b32_e32 v64, v225
	v_mov_b32_e32 v63, v225
	v_mov_b32_e32 v62, v225
	v_mov_b32_e32 v61, v225
	v_mov_b32_e32 v60, v225
	v_mov_b32_e32 v59, v225
	v_mov_b32_e32 v58, v225
	v_mov_b32_e32 v57, v225
	v_mov_b32_e32 v56, v225
	v_mov_b32_e32 v55, v225
	v_mov_b32_e32 v54, v225
	v_mov_b32_e32 v53, v225
	v_mov_b32_e32 v52, v225
	v_mov_b32_e32 v51, v225
	v_mov_b32_e32 v50, v225
	v_mov_b32_e32 v49, v225
	v_mov_b32_e32 v48, v225
	v_mov_b32_e32 v31, v225
	v_mov_b32_e32 v30, v225
	v_mov_b32_e32 v29, v225
	v_mov_b32_e32 v28, v225
	v_mov_b32_e32 v27, v225
	v_mov_b32_e32 v26, v225
	v_mov_b32_e32 v25, v225
	v_mov_b32_e32 v24, v225
	v_mov_b32_e32 v23, v225
	v_mov_b32_e32 v22, v225
	v_mov_b32_e32 v21, v225
	v_mov_b32_e32 v20, v225
	v_mov_b32_e32 v19, v225
	v_mov_b32_e32 v18, v225
	v_mov_b32_e32 v17, v225
	v_mov_b32_e32 v16, v225
	v_mov_b32_e32 v15, v225
	v_mov_b32_e32 v14, v225
	v_mov_b32_e32 v13, v225
	v_mov_b32_e32 v12, v225
	v_mov_b32_e32 v11, v225
	v_mov_b32_e32 v10, v225
	v_mov_b32_e32 v9, v225
	v_mov_b32_e32 v8, v225
	v_mov_b32_e32 v7, v225
	v_mov_b32_e32 v6, v225
	v_mov_b32_e32 v5, v225
	v_mov_b32_e32 v4, v225
	v_mov_b32_e32 v127, v225
	v_mov_b32_e32 v126, v225
	v_mov_b32_e32 v125, v225
	v_mov_b32_e32 v124, v225
	v_mov_b32_e32 v123, v225
	v_mov_b32_e32 v122, v225
	v_mov_b32_e32 v121, v225
	v_mov_b32_e32 v120, v225
	v_mov_b32_e32 v119, v225
	v_mov_b32_e32 v118, v225
	v_mov_b32_e32 v117, v225
	v_mov_b32_e32 v116, v225
	v_mov_b32_e32 v115, v225
	v_mov_b32_e32 v114, v225
	s_waitcnt vmcnt(0)
	v_cvt_i32_f32_e32 v1, v0
	v_cmp_gt_f32_e32 vcc, s78, v0
	v_mov_b32_e32 v113, v225
	v_mov_b32_e32 v112, v225
	v_readfirstlane_b32 s18, v1
	s_not_b32 s63, s18
	s_add_i32 s18, s62, s63
	s_max_i32 s18, s18, 0
	s_lshr_b32 s18, s18, 6
	s_and_b64 s[64:65], vcc, exec
	s_cselect_b32 s64, s18, 0
	s_add_i32 s84, s62, s75
	s_lshl_b64 s[66:67], s[8:9], 2
	s_add_u32 s86, s73, s66
	s_addc_u32 s87, s74, s67
	s_ashr_i32 s9, s84, 31
	s_add_u32 s82, s84, s76
	s_addc_u32 s83, s9, 0
	s_lshl_b32 s18, s8, 7
	s_lshl_b32 s8, s8, 8
	s_lshl_b32 s65, s64, 18
	s_add_i32 s8, s65, s8
	v_add_u32_e32 v0, s18, v231
	v_add_u32_e32 v210, s8, v232
	s_lshl_b32 s66, s64, 7
	v_lshl_or_b32 v2, v0, 13, v218
	v_lshl_add_u64 v[0:1], s[38:39], 0, v[210:211]
	v_or_b32_e32 v32, s82, v214
	v_mov_b32_e32 v33, s83
	global_load_dwordx4 v[160:163], v210, s[38:39]
	v_add_u32_e32 v210, s66, v2
	v_add_co_u32_e64 v0, s[8:9], s79, v0
	v_lshlrev_b64 v[32:33], 12, v[32:33]
	s_nop 0
	v_addc_co_u32_e64 v1, s[8:9], 0, v1, s[8:9]
	v_lshl_add_u64 v[2:3], s[36:37], 0, v[210:211]
	v_lshl_add_u64 v[32:33], s[34:35], 0, v[32:33]
	global_load_dword v34, v211, s[86:87]
	global_load_dwordx4 v[164:167], v210, s[36:37]
	global_load_dwordx4 v[168:171], v[0:1], off
	v_add_co_u32_e64 v0, s[8:9], s80, v2
	v_lshl_add_u64 v[32:33], s[18:19], 1, v[32:33]
	s_nop 0
	v_addc_co_u32_e64 v1, s[8:9], 0, v3, s[8:9]
	v_lshl_add_u64 v[32:33], v[32:33], 0, v[222:223]
	global_load_dwordx4 v[172:175], v[0:1], off
	global_load_dwordx4 v[176:179], v[32:33], off
	global_load_dwordx4 v[180:183], v[32:33], off offset:32
	global_load_dwordx4 v[184:187], v[32:33], off offset:64
	global_load_dwordx4 v[188:191], v[32:33], off offset:96
	global_load_dwordx4 v[192:195], v[32:33], off offset:128
	global_load_dwordx4 v[196:199], v[32:33], off offset:160
	global_load_dwordx4 v[200:203], v[32:33], off offset:192
	global_load_dwordx4 v[204:207], v[32:33], off offset:224
	s_lshl_b32 s85, s11, 2
	s_add_i32 s85, s85, 4
	s_bitcmp1_b32 s64, 0
	s_cselect_b32 s8, 0x4400, 0
	s_add_i32 s8, s8, 0
	v_add_u32_e32 v33, s8, v220
	v_add_u32_e32 v32, s8, v216
	v_add_u32_e32 v35, 0x8800, v33
	v_add_u32_e32 v33, 0xaa00, v33
	v_mov_b32_e32 v3, v225
	v_mov_b32_e32 v2, v225
	v_mov_b32_e32 v1, v225
	v_mov_b32_e32 v0, v225
	v_mov_b32_e32 v111, v225
	v_mov_b32_e32 v110, v225
	v_mov_b32_e32 v109, v225
	v_mov_b32_e32 v108, v225
	v_mov_b32_e32 v107, v225
	v_mov_b32_e32 v106, v225
	v_mov_b32_e32 v105, v225
	v_mov_b32_e32 v104, v225
	v_mov_b32_e32 v103, v225
	v_mov_b32_e32 v102, v225
	v_mov_b32_e32 v101, v225
	v_mov_b32_e32 v100, v225
	v_mov_b32_e32 v99, v225
	v_mov_b32_e32 v98, v225
	v_mov_b32_e32 v97, v225
	v_mov_b32_e32 v96, v225
	v_mov_b32_e32 v95, v225
	v_mov_b32_e32 v94, v225
	v_mov_b32_e32 v93, v225
	v_mov_b32_e32 v92, v225
	v_mov_b32_e32 v91, v225
	s_cmp_ge_i32 s64, s85
	v_mov_b32_e32 v90, v225
	v_mov_b32_e32 v89, v225
	v_mov_b32_e32 v88, v225
	v_mov_b32_e32 v87, v225
	v_mov_b32_e32 v86, v225
	v_mov_b32_e32 v85, v225
	v_mov_b32_e32 v84, v225
	v_mov_b32_e32 v83, v225
	v_mov_b32_e32 v82, v225
	v_mov_b32_e32 v81, v225
	v_mov_b32_e32 v80, v225
	v_mov_b32_e32 v47, v225
	v_mov_b32_e32 v46, v225
	v_mov_b32_e32 v45, v225
	v_mov_b32_e32 v44, v225
	s_waitcnt vmcnt(12)
	ds_write_b128 v32, v[160:163]
	s_waitcnt vmcnt(9)
	ds_write_b128 v32, v[168:171] offset:8704
	ds_write2_b64 v35, v[164:165], v[166:167] offset1:1
	s_waitcnt vmcnt(8)
	ds_write2_b64 v33, v[172:173], v[174:175] offset1:1
	v_readfirstlane_b32 s86, v34
	v_mov_b32_e32 v43, v225
	v_mov_b32_e32 v42, v225
	v_mov_b32_e32 v41, v225
	v_mov_b32_e32 v40, v225
	v_mov_b32_e32 v39, v225
	v_mov_b32_e32 v38, v225
	v_mov_b32_e32 v37, v225
	v_mov_b32_e32 v36, v225
	v_mov_b32_e32 v35, v225
	v_mov_b32_e32 v34, v225
	v_mov_b32_e32 v33, v225
	v_mov_b32_e32 v32, v225
	s_waitcnt lgkmcnt(0)
	s_barrier
; #define AT_LOADK(tt) do { const unsigned ko = kgo + (unsigned)(tt) * (64 * BR * 2); ks0 = *(const u32x4*)((const char*)K + ko); ks1 = *(const u32x4*)((const char*)K + ko + 32 * BR * 2); } while (0)
; #define AT_LOADV(tt) do { const unsigned vo = vgo + (unsigned)(tt) * 128; vs0 = *(const u32x4*)((const char*)Vt + vo); vs1 = *(const u32x4*)((const char*)Vt + vo + 64 * SEQ * 2); } while (0)
; #define AT_WRITEK(buf) do { *(LAS u32x4*)(lds + (buf) * KT_BYTES + kl) = ks0; *(LAS u32x4*)(lds + (buf) * KT_BYTES + kl + 32 * KROW) = ks1; } while (0)
; __device__ __forceinline__ void attn_unit(int b, int h, int qb, bf16_t* Q, const bf16_t* __restrict__ K, const bf16_t* __restrict__ Vt, const bf16_t* __restrict__ Z, const float* __restrict__ hg, float lam, ...
;     ...
;     const int NT = 4 * (qb + 1), last_w = (qw0 + 31) >> 6;
;     int tlo_w = 0; if (Dwin < 4096.f) { const int kmin_w = qw0 - (int)Dwin - 1; tlo_w = kmin_w > 0 ? (kmin_w >> 6) : 0; }
;     f32x16 o[2][4];
; #pragma unroll
;     for (int s = 0; s < 2; ++s)
; #pragma unroll
;         for (int d = 0; d < 4; ++d)
; #pragma unroll
;             for (int r = 0; r < 16; ++r) o[s][d][r] = 0.f;
;     float lsum[2] = {0.f, 0.f};
;     ...
;         if (more) AT_LOADK(t + 1);
;         __builtin_amdgcn_sched_barrier(0);
;         if (active) att_half<0>(o, lsum, qf, kb, vb, slope2, SB, 64 * t, qw0, r32, hi, band, more, ks0, ks1, lds + (cur ^ 1) * KT_BYTES + kl);
;         else if (more) AT_WRITEK(cur ^ 1);
;         __builtin_amdgcn_sched_barrier(0);
;         if (more) AT_LOADV(t + 1);
	s_cbranch_scc1 .LBB0_236
	s_add_i32 s8, s84, s63
	s_max_i32 s8, s8, 0
	s_ashr_i32 s87, s84, 6
	s_lshr_b32 s11, s8, 6
	s_and_b64 s[8:9], vcc, exec
	s_cselect_b32 s88, s11, 0
	v_add_u32_e32 v0, s62, v239
	s_lshl_b32 s89, s64, 6
	v_subrev_u32_e32 v223, s89, v0
	v_add_u32_e32 v0, s62, v238
	v_sub_u32_e32 v246, v237, v0
	v_add_u32_e32 v0, s66, v240
	s_lshl_b32 s8, s10, 20
	v_subrev_u32_e32 v226, s8, v0
	v_add_u32_e32 v0, s65, v241
	s_lshl_b32 s8, s10, 8
	v_mov_b32_e32 v32, v211
	v_mov_b32_e32 v33, v211
	v_mov_b32_e32 v46, v211
	v_mov_b32_e32 v47, v211
	v_subrev_u32_e32 v210, s8, v0
	v_mov_b32_e32 v34, v211
	v_mov_b32_e32 v35, v211
	v_mov_b32_e32 v36, v211
	v_mov_b32_e32 v37, v211
	v_mov_b32_e32 v38, v211
	v_mov_b32_e32 v39, v211
	v_mov_b32_e32 v40, v211
	v_mov_b32_e32 v41, v211
	v_mov_b32_e32 v42, v211
	v_mov_b32_e32 v43, v211
	v_mov_b32_e32 v44, v211
	v_mov_b32_e32 v45, v211
	v_mov_b32_e32 v224, 0
	v_mov_b64_e32 v[94:95], v[46:47]
	v_mov_b64_e32 v[110:111], v[46:47]
	v_mov_b64_e32 v[126:127], v[46:47]
	v_mov_b64_e32 v[0:1], v[32:33]
	v_mov_b64_e32 v[16:17], v[32:33]
	v_mov_b64_e32 v[62:63], v[46:47]
	v_mov_b64_e32 v[78:79], v[46:47]
	v_mov_b64_e32 v[92:93], v[44:45]
	v_mov_b64_e32 v[90:91], v[42:43]
	v_mov_b64_e32 v[88:89], v[40:41]
	v_mov_b64_e32 v[86:87], v[38:39]
	v_mov_b64_e32 v[84:85], v[36:37]
	v_mov_b64_e32 v[82:83], v[34:35]
	v_mov_b64_e32 v[80:81], v[32:33]
	v_mov_b64_e32 v[108:109], v[44:45]
	v_mov_b64_e32 v[106:107], v[42:43]
	v_mov_b64_e32 v[104:105], v[40:41]
	v_mov_b64_e32 v[102:103], v[38:39]
	v_mov_b64_e32 v[100:101], v[36:37]
	v_mov_b64_e32 v[98:99], v[34:35]
	v_mov_b64_e32 v[96:97], v[32:33]
	v_mov_b64_e32 v[124:125], v[44:45]
	v_mov_b64_e32 v[122:123], v[42:43]
	v_mov_b64_e32 v[120:121], v[40:41]
	v_mov_b64_e32 v[118:119], v[38:39]
	v_mov_b64_e32 v[116:117], v[36:37]
	v_mov_b64_e32 v[114:115], v[34:35]
	v_mov_b64_e32 v[112:113], v[32:33]
	v_mov_b64_e32 v[2:3], v[34:35]
	v_mov_b64_e32 v[4:5], v[36:37]
	v_mov_b64_e32 v[6:7], v[38:39]
	v_mov_b64_e32 v[8:9], v[40:41]
	v_mov_b64_e32 v[10:11], v[42:43]
	v_mov_b64_e32 v[12:13], v[44:45]
	v_mov_b64_e32 v[14:15], v[46:47]
	v_mov_b64_e32 v[18:19], v[34:35]
	v_mov_b64_e32 v[20:21], v[36:37]
	v_mov_b64_e32 v[22:23], v[38:39]
	v_mov_b64_e32 v[24:25], v[40:41]
	v_mov_b64_e32 v[26:27], v[42:43]
	v_mov_b64_e32 v[28:29], v[44:45]
	v_mov_b64_e32 v[30:31], v[46:47]
	v_mov_b64_e32 v[60:61], v[44:45]
	v_mov_b64_e32 v[58:59], v[42:43]
	v_mov_b64_e32 v[56:57], v[40:41]
	v_mov_b64_e32 v[54:55], v[38:39]
	v_mov_b64_e32 v[52:53], v[36:37]
	v_mov_b64_e32 v[50:51], v[34:35]
	v_mov_b64_e32 v[48:49], v[32:33]
	v_mov_b64_e32 v[76:77], v[44:45]
	v_mov_b64_e32 v[74:75], v[42:43]
	v_mov_b64_e32 v[72:73], v[40:41]
	v_mov_b64_e32 v[70:71], v[38:39]
	v_mov_b64_e32 v[68:69], v[36:37]
	v_mov_b64_e32 v[66:67], v[34:35]
	v_mov_b64_e32 v[64:65], v[32:33]
	v_mov_b32_e32 v225, v224
	global_load_dwordx4 v[160:163], v210, s[38:39]
	v_add_u32_e32 v128, 0x20000, v210
	global_load_dwordx4 v[168:171], v128, s[38:39]
	global_load_dwordx4 v[164:167], v226, s[36:37]
	v_add_u32_e32 v128, 0x80000, v226
	global_load_dwordx4 v[172:175], v128, s[36:37]

; #define LAS __attribute__((address_space(3)))
; #define AT_LOADK(tt) do { const unsigned ko = kgo + (unsigned)(tt) * (64 * BR * 2); ks0 = *(const u32x4*)((const char*)K + ko); ks1 = *(const u32x4*)((const char*)K + ko + 32 * BR * 2); } while (0)
; #define AT_LOADV(tt) do { const unsigned vo = vgo + (unsigned)(tt) * 128; vs0 = *(const u32x4*)((const char*)Vt + vo); vs1 = *(const u32x4*)((const char*)Vt + vo + 64 * SEQ * 2); } while (0)
; #define AT_WRITEK(buf) do { *(LAS u32x4*)(lds + (buf) * KT_BYTES + kl) = ks0; *(LAS u32x4*)(lds + (buf) * KT_BYTES + kl + 32 * KROW) = ks1; } while (0)
; #define AT_WRITEV(buf) do { \
;         *(LAS u32x2*)(lds + (buf) * VT_BYTES + vl) = (u32x2){vs0.x, vs0.y}; *(LAS u32x2*)(lds + (buf) * VT_BYTES + vl + 8) = (u32x2){vs0.z, vs0.w}; \
;         *(LAS u32x2*)(lds + (buf) * VT_BYTES + vl + 64 * VROW) = (u32x2){vs1.x, vs1.y}; *(LAS u32x2*)(lds + (buf) * VT_BYTES + vl + 64 * VROW + 8) = (u32x2){vs1.z, vs1.w}; } while (0)
; __device__ __forceinline__ void attn_unit(int b, int h, int qb, bf16_t* Q, const bf16_t* __restrict__ K, const bf16_t* __restrict__ Vt, const bf16_t* __restrict__ Z, const float* __restrict__ hg, float lam, ...
;     ...
;     AT_LOADK(tfirst); AT_LOADV(tfirst); AT_WRITEK(tfirst & 1); AT_WRITEV(tfirst & 1);
;     __syncthreads();
;     for (int t = tfirst; t < NT; ++t) {
;         const int cur = t & 1; const bool more = (t + 1 < NT), active = (t <= last_w) && (t >= tlo_w), band = (64 * t + 63 > qw0);
;         const LAS unsigned char* kb = lds + cur * KT_BYTES + r32 * KROW + hi * 16;
;         const LAS unsigned char* vb = lds + AT_VOFF + cur * VT_BYTES + r32 * VROW + hi * 8;
;         if (more) AT_LOADK(t + 1);
;         __builtin_amdgcn_sched_barrier(0);
;         if (active) att_half<0>(o, lsum, qf, kb, vb, slope2, SB, 64 * t, qw0, r32, hi, band, more, ks0, ks1, lds + (cur ^ 1) * KT_BYTES + kl);
;         else if (more) AT_WRITEK(cur ^ 1);
.LBB0_247:
	s_and_b32 s92, s64, 1
	s_cmp_le_i32 s64, s87
	s_cselect_b64 s[10:11], -1, 0
	s_cmp_ge_i32 s64, s88
	s_cselect_b64 s[64:65], -1, 0
	s_and_b64 s[64:65], s[10:11], s[64:65]
	s_add_i32 s10, s89, 63
	s_cmp_gt_i32 s10, s84
	s_cselect_b64 s[10:11], -1, 0
	v_cndmask_b32_e64 v128, 0, 1, s[8:9]
	s_mov_b64 s[66:67], -1
	s_andn2_b64 vcc, exec, s[64:65]
	v_cmp_ne_u32_e64 s[8:9], 1, v128
	s_cbranch_vccz .LBB0_251
	s_and_b64 vcc, exec, s[8:9]
	s_cbranch_vccnz .LBB0_250
	s_xor_b32 s66, s92, 1
	s_mulk_i32 s66, 0x4400
	v_add_u32_e32 v128, s66, v233
	s_waitcnt vmcnt(3)
	ds_write_b128 v128, v[160:163]
	s_waitcnt vmcnt(2)
	ds_write_b128 v128, v[168:171] offset:8704
	v_add_u32_e32 v128, 0x40000, v210
	v_add_u32_e32 v129, 0x60000, v210
	global_load_dwordx4 v[160:163], v128, s[38:39]
	global_load_dwordx4 v[168:171], v129, s[38:39]

; #define LAS __attribute__((address_space(3)))
; __device__ __forceinline__ unsigned cvtpk_s(float lo, float hi) { f32x2_t v = {lo, hi}; bf16x2_t b = __builtin_convertvector(v, bf16x2_t); return __builtin_bit_cast(unsigned, b); }
; template <int HF> ...
;     ...
;         for (int d0 = 0; d0 < 4; ++d0) { const bf16x8 kf = *(const LAS bf16x8*)(kb + HF * 32 * KROW + sub * 128 + d0 * 32);
;             p = __builtin_amdgcn_mfma_f32_32x32x16_bf16(kf, qf[sub][d0], p, 0, 0, 0); }
;         if (band) { const int lim = qw0 + r32 - (kvh0 + 4 * hi);
;             asm volatile("s_nop 15" : "+v"(p));
;             const float ninf = -INFINITY;
; #pragma unroll
;             for (int r = 0; r < 16; ++r) asm("v_cmp_gt_i32_e32 vcc, %2, %1\n\tv_cndmask_b32_e32 %0, %0, %3, vcc" : "+v"(p[r]) : "v"(lim), "i"((r & 3) + 8 * (r >> 2)), "v"(ninf) : "vcc"); }
;         float ls = 0.f;
; #pragma unroll
;         for (int r = 0; r < 16; ++r) { p[r] = __builtin_amdgcn_exp2f(p[r]); ls += p[r]; }
;         lsum[sub] += ls;
;         pw[sub][0] = (u32x4){cvtpk_s(p[0], p[1]), cvtpk_s(p[2], p[3]), cvtpk_s(p[4], p[5]), cvtpk_s(p[6], p[7])};
;         pw[sub][1] = (u32x4){cvtpk_s(p[8], p[9]), cvtpk_s(p[10], p[11]), cvtpk_s(p[12], p[13]), cvtpk_s(p[14], p[15])};
;         __builtin_amdgcn_sched_barrier(0);
;         if (sub == 0 && stage) {
;             if (HF == 0) { *(LAS u32x4*)sdst = st0; *(LAS u32x4*)(sdst + 32 * KROW) = st1; }
;             else { *(LAS u32x2*)sdst = (u32x2){st0.x, st0.y}; *(LAS u32x2*)(sdst + 8) = (u32x2){st0.z, st0.w}; *(LAS u32x2*)(sdst + 64 * VROW) = (u32x2){st1.x, st1.y}; *(LAS u32x2*)(sdst + 64 * VROW + 8) = (u32x2){st1.z, st1.w}; }
;             __builtin_amdgcn_sched_barrier(0);
.LBB0_254:
	s_and_b64 vcc, exec, s[8:9]
	s_cbranch_vccnz .LBB0_256
	s_xor_b32 s66, s92, 1
	s_mulk_i32 s66, 0x4400
	v_add_u32_e32 v248, s66, v233
	s_waitcnt vmcnt(3)
	ds_write_b128 v248, v[160:163]
	s_waitcnt vmcnt(2)
	ds_write_b128 v248, v[168:171] offset:8704
	v_add_u32_e32 v254, 0x40000, v210
	v_add_u32_e32 v255, 0x60000, v210
	global_load_dwordx4 v[160:163], v254, s[38:39]
	global_load_dwordx4 v[168:171], v255, s[38:39]
.LBB0_256:
	ds_read_b128 v[248:251], v247 offset:128
	ds_read_b128 v[252:255], v247 offset:160
	s_and_b64 vcc, exec, s[10:11]
	s_waitcnt lgkmcnt(1)
	v_mfma_f32_32x32x16_bf16 v[128:143], v[248:251], v[192:195], v[128:143]
	s_waitcnt lgkmcnt(0)
	v_mfma_f32_32x32x16_bf16 v[128:143], v[252:255], v[196:199], v[128:143]
	ds_read_b128 v[248:251], v247 offset:192
	ds_read_b128 v[252:255], v247 offset:224
	s_waitcnt lgkmcnt(1)
	v_mfma_f32_32x32x16_bf16 v[128:143], v[248:251], v[200:203], v[128:143]
	s_waitcnt lgkmcnt(0)
	v_mfma_f32_32x32x16_bf16 v[128:143], v[252:255], v[204:207], v[128:143]
	s_cbranch_vccnz .LBB0_258
	s_nop 15
	s_nop 0
	v_cmp_gt_i32_e32 vcc, 0, v227
	v_cndmask_b32_e32 v128, v128, v244, vcc
	s_nop 0
	v_cmp_gt_i32_e32 vcc, 1, v227
	v_cndmask_b32_e32 v129, v129, v244, vcc
	s_nop 0
	v_cmp_gt_i32_e32 vcc, 2, v227
	v_cndmask_b32_e32 v130, v130, v244, vcc
	s_nop 0
	v_cmp_gt_i32_e32 vcc, 3, v227
	v_cndmask_b32_e32 v131, v131, v244, vcc
	s_nop 0
	v_cmp_gt_i32_e32 vcc, 8, v227
	v_cndmask_b32_e32 v132, v132, v244, vcc
	s_nop 0
	v_cmp_gt_i32_e32 vcc, 9, v227
	v_cndmask_b32_e32 v133, v133, v244, vcc
	s_nop 0
	v_cmp_gt_i32_e32 vcc, 10, v227
	v_cndmask_b32_e32 v134, v134, v244, vcc
	s_nop 0
	v_cmp_gt_i32_e32 vcc, 11, v227
	v_cndmask_b32_e32 v135, v135, v244, vcc
	s_nop 0
	v_cmp_gt_i32_e32 vcc, 16, v227
	v_cndmask_b32_e32 v136, v136, v244, vcc
	s_nop 0
	v_cmp_gt_i32_e32 vcc, 17, v227
	v_cndmask_b32_e32 v137, v137, v244, vcc
	s_nop 0
	v_cmp_gt_i32_e32 vcc, 18, v227
	v_cndmask_b32_e32 v138, v138, v244, vcc
	s_nop 0
	v_cmp_gt_i32_e32 vcc, 19, v227
	v_cndmask_b32_e32 v139, v139, v244, vcc
	s_nop 0
	v_cmp_gt_i32_e32 vcc, 24, v227
	v_cndmask_b32_e32 v140, v140, v244, vcc
	s_nop 0
	v_cmp_gt_i32_e32 vcc, 25, v227
	v_cndmask_b32_e32 v141, v141, v244, vcc
	s_nop 0
	v_cmp_gt_i32_e32 vcc, 26, v227
	v_cndmask_b32_e32 v142, v142, v244, vcc
	s_nop 0
	v_cmp_gt_i32_e32 vcc, 27, v227
	v_cndmask_b32_e32 v143, v143, v244, vcc

; #define AT_LOADV(tt) do { const unsigned vo = vgo + (unsigned)(tt) * 128; vs0 = *(const u32x4*)((const char*)Vt + vo); vs1 = *(const u32x4*)((const char*)Vt + vo + 64 * SEQ * 2); } while (0)
; #define AT_WRITEV(buf) do { \
;         *(LAS u32x2*)(lds + (buf) * VT_BYTES + vl) = (u32x2){vs0.x, vs0.y}; *(LAS u32x2*)(lds + (buf) * VT_BYTES + vl + 8) = (u32x2){vs0.z, vs0.w}; \
;         *(LAS u32x2*)(lds + (buf) * VT_BYTES + vl + 64 * VROW) = (u32x2){vs1.x, vs1.y}; *(LAS u32x2*)(lds + (buf) * VT_BYTES + vl + 64 * VROW + 8) = (u32x2){vs1.z, vs1.w}; } while (0)
; __device__ __forceinline__ void attn_unit(int b, int h, int qb, bf16_t* Q, const bf16_t* __restrict__ K, const bf16_t* __restrict__ Vt, const bf16_t* __restrict__ Z, const float* __restrict__ hg, float lam, ...
;     ...
;         if (more) AT_LOADV(t + 1);
;         __builtin_amdgcn_sched_barrier(0);
;         if (active && (64 * t + 32 <= qw0 + 31)) att_half<1>(o, lsum, qf, kb, vb, slope2, SB, 64 * t + 32, qw0, r32, hi, band, more, vs0, vs1, lds + (cur ^ 1) * VT_BYTES + vl);
;         else if (more) AT_WRITEV(cur ^ 1);
.LBB0_261:
	s_cmp_lt_i32 s89, s84
	s_cselect_b64 s[66:67], -1, 0
	s_and_b64 s[64:65], s[64:65], s[66:67]
	s_andn2_b64 vcc, exec, s[64:65]
	s_mov_b64 s[64:65], -1
	s_cbranch_vccz .LBB0_265
	s_and_b64 vcc, exec, s[8:9]
	s_cbranch_vccnz .LBB0_264
	s_xor_b32 s64, s92, 1
	s_mulk_i32 s64, 0x4400
	v_add_u32_e32 v128, s64, v234
	v_add_u32_e32 v129, 0x8800, v128
	v_add_u32_e32 v128, 0xaa00, v128
	s_waitcnt vmcnt(3)
	ds_write2_b64 v129, v[164:165], v[166:167] offset1:1
	s_waitcnt vmcnt(2)
	ds_write2_b64 v128, v[172:173], v[174:175] offset1:1
	v_add_u32_e32 v128, 0x80, v226
	v_add_u32_e32 v129, 0x80080, v226
	global_load_dwordx4 v[164:167], v128, s[36:37]
	global_load_dwordx4 v[172:175], v129, s[36:37]

; #define LAS __attribute__((address_space(3)))
; __device__ __forceinline__ unsigned cvtpk_s(float lo, float hi) { f32x2_t v = {lo, hi}; bf16x2_t b = __builtin_convertvector(v, bf16x2_t); return __builtin_bit_cast(unsigned, b); }
; template <int HF> ...
;     ...
;         for (int d0 = 0; d0 < 4; ++d0) { const bf16x8 kf = *(const LAS bf16x8*)(kb + HF * 32 * KROW + sub * 128 + d0 * 32);
;             p = __builtin_amdgcn_mfma_f32_32x32x16_bf16(kf, qf[sub][d0], p, 0, 0, 0); }
;         if (band) { const int lim = qw0 + r32 - (kvh0 + 4 * hi);
;             asm volatile("s_nop 15" : "+v"(p));
;             const float ninf = -INFINITY;
; #pragma unroll
;             for (int r = 0; r < 16; ++r) asm("v_cmp_gt_i32_e32 vcc, %2, %1\n\tv_cndmask_b32_e32 %0, %0, %3, vcc" : "+v"(p[r]) : "v"(lim), "i"((r & 3) + 8 * (r >> 2)), "v"(ninf) : "vcc"); }
;         float ls = 0.f;
; #pragma unroll
;         for (int r = 0; r < 16; ++r) { p[r] = __builtin_amdgcn_exp2f(p[r]); ls += p[r]; }
;         lsum[sub] += ls;
;         pw[sub][0] = (u32x4){cvtpk_s(p[0], p[1]), cvtpk_s(p[2], p[3]), cvtpk_s(p[4], p[5]), cvtpk_s(p[6], p[7])};
;         pw[sub][1] = (u32x4){cvtpk_s(p[8], p[9]), cvtpk_s(p[10], p[11]), cvtpk_s(p[12], p[13]), cvtpk_s(p[14], p[15])};
;         __builtin_amdgcn_sched_barrier(0);
;         if (sub == 0 && stage) {
;             if (HF == 0) { *(LAS u32x4*)sdst = st0; *(LAS u32x4*)(sdst + 32 * KROW) = st1; }
;             else { *(LAS u32x2*)sdst = (u32x2){st0.x, st0.y}; *(LAS u32x2*)(sdst + 8) = (u32x2){st0.z, st0.w}; *(LAS u32x2*)(sdst + 64 * VROW) = (u32x2){st1.x, st1.y}; *(LAS u32x2*)(sdst + 64 * VROW + 8) = (u32x2){st1.z, st1.w}; }
;             __builtin_amdgcn_sched_barrier(0);
.LBB0_268:
	s_and_b64 vcc, exec, s[8:9]
	s_cbranch_vccnz .LBB0_270
	s_xor_b32 s8, s92, 1
	s_mulk_i32 s8, 0x4400
	v_add_u32_e32 v227, s8, v234
	v_add_u32_e32 v248, 0x8800, v227
	v_add_u32_e32 v227, 0xaa00, v227
	s_waitcnt vmcnt(3)
	ds_write2_b64 v248, v[164:165], v[166:167] offset1:1
	s_waitcnt vmcnt(2)
	ds_write2_b64 v227, v[172:173], v[174:175] offset1:1
	v_add_u32_e32 v254, 0x80, v226
	v_add_u32_e32 v255, 0x80080, v226
	global_load_dwordx4 v[164:167], v254, s[36:37]
	global_load_dwordx4 v[172:175], v255, s[36:37]
.LBB0_270:
	ds_read_b128 v[248:251], v247 offset:8832
	ds_read_b128 v[252:255], v247 offset:8864
	s_and_b64 vcc, exec, s[10:11]
	s_waitcnt lgkmcnt(1)
	v_mfma_f32_32x32x16_bf16 v[128:143], v[248:251], v[192:195], v[128:143]
	s_waitcnt lgkmcnt(0)
	v_mfma_f32_32x32x16_bf16 v[128:143], v[252:255], v[196:199], v[128:143]
	ds_read_b128 v[248:251], v247 offset:8896
	ds_read_b128 v[252:255], v247 offset:8928
	s_waitcnt lgkmcnt(1)
	v_mfma_f32_32x32x16_bf16 v[128:143], v[248:251], v[200:203], v[128:143]
	s_waitcnt lgkmcnt(0)
	v_mfma_f32_32x32x16_bf16 v[128:143], v[252:255], v[204:207], v[128:143]
	s_cbranch_vccnz .LBB0_272
	s_nop 15
	s_nop 0
	v_cmp_gt_i32_e32 vcc, 0, v223
	v_cndmask_b32_e32 v128, v128, v244, vcc
	s_nop 0
	v_cmp_gt_i32_e32 vcc, 1, v223
	v_cndmask_b32_e32 v129, v129, v244, vcc
	s_nop 0
	v_cmp_gt_i32_e32 vcc, 2, v223
	v_cndmask_b32_e32 v130, v130, v244, vcc
	s_nop 0
	v_cmp_gt_i32_e32 vcc, 3, v223
	v_cndmask_b32_e32 v131, v131, v244, vcc
	s_nop 0
	v_cmp_gt_i32_e32 vcc, 8, v223
	v_cndmask_b32_e32 v132, v132, v244, vcc
	s_nop 0
	v_cmp_gt_i32_e32 vcc, 9, v223
	v_cndmask_b32_e32 v133, v133, v244, vcc
	s_nop 0
	v_cmp_gt_i32_e32 vcc, 10, v223
	v_cndmask_b32_e32 v134, v134, v244, vcc
	s_nop 0
	v_cmp_gt_i32_e32 vcc, 11, v223
	v_cndmask_b32_e32 v135, v135, v244, vcc
	s_nop 0
	v_cmp_gt_i32_e32 vcc, 16, v223
	v_cndmask_b32_e32 v136, v136, v244, vcc
	s_nop 0
	v_cmp_gt_i32_e32 vcc, 17, v223
	v_cndmask_b32_e32 v137, v137, v244, vcc
	s_nop 0
	v_cmp_gt_i32_e32 vcc, 18, v223
	v_cndmask_b32_e32 v138, v138, v244, vcc
	s_nop 0
	v_cmp_gt_i32_e32 vcc, 19, v223
	v_cndmask_b32_e32 v139, v139, v244, vcc
	s_nop 0
	v_cmp_gt_i32_e32 vcc, 24, v223
	v_cndmask_b32_e32 v140, v140, v244, vcc
	s_nop 0
	v_cmp_gt_i32_e32 vcc, 25, v223
	v_cndmask_b32_e32 v141, v141, v244, vcc
	s_nop 0
	v_cmp_gt_i32_e32 vcc, 26, v223
	v_cndmask_b32_e32 v142, v142, v244, vcc
	s_nop 0
	v_cmp_gt_i32_e32 vcc, 27, v223
	v_cndmask_b32_e32 v143, v143, v244, vcc

; __device__ __forceinline__ float siluf_(float v) { return v * __builtin_amdgcn_rcpf(1.f + __builtin_amdgcn_exp2f(-LOG2E * v)); }
;     __device__ __forceinline__ void operator()(const AccT& acc, const Unit& u, int wr, int wc, int fr, int fq) const {
;         const int kind = u.pn >> 3, tile = u.pn & 7; bf16_t* base = kind ? Zs : U;
;         const int row0 = u.pm * 256 + wr * 64 + fr, col0 = tile * 256 + wc * 32 + 8 * fq;
; #pragma unroll
;         for (int ai = 0; ai < 2; ++ai)
; #pragma unroll
;             for (int m = 0; m < 4; ++m) { const int row = row0 + ai * 128 + m * 16; const float rs = rsqrtf(rowss[row] * (1.f / DM) + EPS);
; #pragma unroll
;                 for (int bj = 0; bj < 2; ++bj) { f32x4 v0 = acc[ai][bj][m][0] * rs, v1 = acc[ai][bj][m][1] * rs;
;                     if (kind) {
; #pragma unroll
;                         for (int j = 0; j < 4; ++j) { v0[j] = siluf_(v0[j]); v1[j] = siluf_(v1[j]); } }
.LBB0_355:
	v_lshl_add_u32 v148, s8, 8, v158
	v_ashrrev_i32_e32 v149, 31, v148
	v_lshl_add_u64 v[150:151], v[148:149], 2, s[50:51]
	global_load_dword v138, v[150:151], off
	global_load_dword v233, v[150:151], off offset:64
	global_load_dword v234, v[150:151], off offset:128
	global_load_dword v235, v[150:151], off offset:192
	global_load_dword v236, v[150:151], off offset:512
	global_load_dword v237, v[150:151], off offset:576
	global_load_dword v238, v[150:151], off offset:640
	global_load_dword v239, v[150:151], off offset:704
	s_cmp_lt_u32 s10, 8
	s_cselect_b64 s[64:65], -1, 0
	s_cmp_gt_u32 s10, 7
	s_cselect_b64 s[62:63], -1, 0
	s_and_b64 s[8:9], exec, s[64:65]
	s_waitcnt vmcnt(0)
	v_fmamk_f32 v138, v138, 0x3a800000, v164
	v_mul_f32_e32 v152, 0x4b800000, v138
	v_cmp_gt_f32_e32 vcc, s85, v138
	s_nop 1
	v_cndmask_b32_e32 v138, v138, v152, vcc
	v_rsq_f32_e32 v138, v138
	s_nop 0
	v_mul_f32_e32 v152, 0x45800000, v138
	v_cndmask_b32_e32 v152, v138, v152, vcc
	v_pk_mul_f32 v[126:127], v[126:127], v[152:153] op_sel_hi:[1,0]
	v_pk_mul_f32 v[156:157], v[124:125], v[152:153] op_sel_hi:[1,0]
	v_pk_mul_f32 v[124:125], v[122:123], v[152:153] op_sel_hi:[1,0]
	v_pk_mul_f32 v[154:155], v[120:121], v[152:153] op_sel_hi:[1,0]
	s_mov_b64 vcc, s[8:9]
	s_cbranch_vccnz .LBB0_357
	v_mul_f32_e32 v138, 0xbfb8aa3b, v126
	v_mul_f32_e32 v121, 0xbfb8aa3b, v154
	v_exp_f32_e32 v138, v138
	v_mul_f32_e32 v153, 0xbfb8aa3b, v124
	v_mul_f32_e32 v122, 0xbfb8aa3b, v157
	v_exp_f32_e32 v121, v121
	v_exp_f32_e32 v153, v153
	v_exp_f32_e32 v123, v122
	v_add_f32_e32 v138, 1.0, v138
	v_add_f32_e32 v121, 1.0, v121
	v_rcp_f32_e32 v166, v138
	v_add_f32_e32 v138, 1.0, v153
	v_mul_f32_e32 v153, 0xbfb8aa3b, v127
	v_mul_f32_e32 v120, 0xbfb8aa3b, v156
	v_rcp_f32_e32 v122, v121
	v_add_f32_e32 v121, 1.0, v123
	v_mul_f32_e32 v123, 0xbfb8aa3b, v155
	v_exp_f32_e32 v153, v153
	v_mul_f32_e32 v165, 0xbfb8aa3b, v125
	v_exp_f32_e32 v120, v120
	v_exp_f32_e32 v123, v123
	v_exp_f32_e32 v165, v165
	v_rcp_f32_e32 v168, v138
	v_add_f32_e32 v138, 1.0, v153
	v_add_f32_e32 v120, 1.0, v120
	v_add_f32_e32 v123, 1.0, v123
	v_rcp_f32_e32 v167, v138
	v_add_f32_e32 v138, 1.0, v165
	v_rcp_f32_e32 v120, v120
	v_rcp_f32_e32 v121, v121
	v_rcp_f32_e32 v169, v138
	v_rcp_f32_e32 v123, v123
	v_pk_mul_f32 v[126:127], v[126:127], v[166:167]
	v_pk_mul_f32 v[156:157], v[156:157], v[120:121]
	v_pk_mul_f32 v[124:125], v[124:125], v[168:169]
	v_pk_mul_f32 v[154:155], v[154:155], v[122:123]

; __device__ __forceinline__ float siluf_(float v) { return v * __builtin_amdgcn_rcpf(1.f + __builtin_amdgcn_exp2f(-LOG2E * v)); }
; __device__ __forceinline__ u32x4 pack8(const f32x4& a, const f32x4& b) { u32x4 w; w.x = pk2(a[0], a[1]); w.y = pk2(a[2], a[3]); w.z = pk2(b[0], b[1]); w.w = pk2(b[2], b[3]); return w; }
;     __device__ __forceinline__ void operator()(const AccT& acc, const Unit& u, int wr, int wc, int fr, int fq) const {
;     ...
;             for (int m = 0; m < 4; ++m) { const int row = row0 + ai * 128 + m * 16; const float rs = rsqrtf(rowss[row] * (1.f / DM) + EPS);
; #pragma unroll
;                 for (int bj = 0; bj < 2; ++bj) { f32x4 v0 = acc[ai][bj][m][0] * rs, v1 = acc[ai][bj][m][1] * rs;
;                     if (kind) {
; #pragma unroll
;                         for (int j = 0; j < 4; ++j) { v0[j] = siluf_(v0[j]); v1[j] = siluf_(v1[j]); } }
;                     __builtin_nontemporal_store(pack8(v0, v1), (u32x4*)(base + (size_t)row * BR + col0 + bj * 128)); } }
.LBB0_359:
	v_cvt_pk_bf16_f32 v116, v116, v117
	v_cvt_pk_bf16_f32 v117, v118, v119
	s_nop 0
	v_cvt_pk_bf16_f32 v118, v112, v113
	v_cvt_pk_bf16_f32 v119, v114, v115
	v_or_b32_e32 v114, 16, v148
	v_ashrrev_i32_e32 v115, 31, v114
	global_store_dwordx4 v[122:123], v[116:119], off offset:256 nt
	v_lshl_add_u64 v[112:113], v[114:115], 2, s[50:51]
	v_mov_b32_e32 v112, v233
	s_and_b64 vcc, exec, s[8:9]
	v_fmamk_f32 v112, v112, 0x3a800000, v164
	v_mul_f32_e32 v113, 0x4b800000, v112
	v_cmp_gt_f32_e64 s[10:11], s85, v112
	s_nop 1
	v_cndmask_b32_e64 v112, v112, v113, s[10:11]
	v_rsq_f32_e32 v112, v112
	s_nop 0
	v_mul_f32_e32 v113, 0x45800000, v112
	v_cndmask_b32_e64 v112, v112, v113, s[10:11]
	v_pk_mul_f32 v[110:111], v[110:111], v[112:113] op_sel_hi:[1,0]
	v_pk_mul_f32 v[116:117], v[108:109], v[112:113] op_sel_hi:[1,0]
	v_pk_mul_f32 v[106:107], v[106:107], v[112:113] op_sel_hi:[1,0]
	v_pk_mul_f32 v[108:109], v[104:105], v[112:113] op_sel_hi:[1,0]
	s_cbranch_vccnz .LBB0_361
	v_mul_f32_e32 v119, 0xbfb8aa3b, v110
	v_mul_f32_e32 v105, 0xbfb8aa3b, v108
	v_exp_f32_e32 v119, v119
	v_mul_f32_e32 v122, 0xbfb8aa3b, v106
	v_mul_f32_e32 v113, 0xbfb8aa3b, v117
	v_exp_f32_e32 v105, v105
	v_exp_f32_e32 v123, v122
	v_exp_f32_e32 v113, v113
	v_add_f32_e32 v119, 1.0, v119
	v_add_f32_e32 v105, 1.0, v105
	v_rcp_f32_e32 v122, v119
	v_add_f32_e32 v119, 1.0, v123
	v_mul_f32_e32 v123, 0xbfb8aa3b, v111
	v_mul_f32_e32 v104, 0xbfb8aa3b, v116
	v_rcp_f32_e32 v118, v105
	v_add_f32_e32 v105, 1.0, v113
	v_mul_f32_e32 v113, 0xbfb8aa3b, v109
	v_exp_f32_e32 v123, v123
	v_mul_f32_e32 v124, 0xbfb8aa3b, v107
	v_exp_f32_e32 v104, v104
	v_exp_f32_e32 v113, v113
	v_exp_f32_e32 v125, v124
	v_rcp_f32_e32 v124, v119
	v_add_f32_e32 v119, 1.0, v123
	v_add_f32_e32 v104, 1.0, v104
	v_add_f32_e32 v113, 1.0, v113
	v_rcp_f32_e32 v123, v119
	v_add_f32_e32 v119, 1.0, v125
	v_rcp_f32_e32 v104, v104
	v_rcp_f32_e32 v105, v105
	v_rcp_f32_e32 v125, v119
	v_rcp_f32_e32 v119, v113
	v_pk_mul_f32 v[110:111], v[110:111], v[122:123]
	v_pk_mul_f32 v[116:117], v[116:117], v[104:105]
	v_pk_mul_f32 v[106:107], v[106:107], v[124:125]
	v_pk_mul_f32 v[108:109], v[108:109], v[118:119]

; __device__ __forceinline__ float siluf_(float v) { return v * __builtin_amdgcn_rcpf(1.f + __builtin_amdgcn_exp2f(-LOG2E * v)); }
; __device__ __forceinline__ u32x4 pack8(const f32x4& a, const f32x4& b) { u32x4 w; w.x = pk2(a[0], a[1]); w.y = pk2(a[2], a[3]); w.z = pk2(b[0], b[1]); w.w = pk2(b[2], b[3]); return w; }
;     __device__ __forceinline__ void operator()(const AccT& acc, const Unit& u, int wr, int wc, int fr, int fq) const {
;     ...
;             for (int m = 0; m < 4; ++m) { const int row = row0 + ai * 128 + m * 16; const float rs = rsqrtf(rowss[row] * (1.f / DM) + EPS);
; #pragma unroll
;                 for (int bj = 0; bj < 2; ++bj) { f32x4 v0 = acc[ai][bj][m][0] * rs, v1 = acc[ai][bj][m][1] * rs;
;                     if (kind) {
; #pragma unroll
;                         for (int j = 0; j < 4; ++j) { v0[j] = siluf_(v0[j]); v1[j] = siluf_(v1[j]); } }
;                     __builtin_nontemporal_store(pack8(v0, v1), (u32x4*)(base + (size_t)row * BR + col0 + bj * 128)); } }
.LBB0_363:
	v_cvt_pk_bf16_f32 v100, v100, v101
	v_cvt_pk_bf16_f32 v101, v102, v103
	s_nop 0
	v_cvt_pk_bf16_f32 v102, v96, v97
	v_cvt_pk_bf16_f32 v103, v98, v99
	v_or_b32_e32 v98, 32, v148
	v_ashrrev_i32_e32 v99, 31, v98
	global_store_dwordx4 v[104:105], v[100:103], off offset:256 nt
	v_lshl_add_u64 v[96:97], v[98:99], 2, s[50:51]
	v_mov_b32_e32 v96, v234
	s_and_b64 vcc, exec, s[8:9]
	v_fmamk_f32 v96, v96, 0x3a800000, v164
	v_mul_f32_e32 v97, 0x4b800000, v96
	v_cmp_gt_f32_e64 s[10:11], s85, v96
	s_nop 1
	v_cndmask_b32_e64 v96, v96, v97, s[10:11]
	v_rsq_f32_e32 v96, v96
	s_nop 0
	v_mul_f32_e32 v97, 0x45800000, v96
	v_cndmask_b32_e64 v96, v96, v97, s[10:11]
	v_pk_mul_f32 v[94:95], v[94:95], v[96:97] op_sel_hi:[1,0]
	v_pk_mul_f32 v[100:101], v[92:93], v[96:97] op_sel_hi:[1,0]
	v_pk_mul_f32 v[90:91], v[90:91], v[96:97] op_sel_hi:[1,0]
	v_pk_mul_f32 v[92:93], v[88:89], v[96:97] op_sel_hi:[1,0]
	s_cbranch_vccnz .LBB0_365
	v_mul_f32_e32 v103, 0xbfb8aa3b, v94
	v_mul_f32_e32 v89, 0xbfb8aa3b, v92
	v_exp_f32_e32 v103, v103
	v_mul_f32_e32 v104, 0xbfb8aa3b, v90
	v_mul_f32_e32 v97, 0xbfb8aa3b, v101
	v_exp_f32_e32 v89, v89
	v_exp_f32_e32 v105, v104
	v_exp_f32_e32 v97, v97
	v_add_f32_e32 v103, 1.0, v103
	v_add_f32_e32 v89, 1.0, v89
	v_rcp_f32_e32 v104, v103
	v_add_f32_e32 v103, 1.0, v105
	v_mul_f32_e32 v105, 0xbfb8aa3b, v95
	v_mul_f32_e32 v88, 0xbfb8aa3b, v100
	v_rcp_f32_e32 v102, v89
	v_add_f32_e32 v89, 1.0, v97
	v_mul_f32_e32 v97, 0xbfb8aa3b, v93
	v_exp_f32_e32 v105, v105
	v_mul_f32_e32 v106, 0xbfb8aa3b, v91
	v_exp_f32_e32 v88, v88
	v_exp_f32_e32 v97, v97
	v_exp_f32_e32 v107, v106
	v_rcp_f32_e32 v106, v103
	v_add_f32_e32 v103, 1.0, v105
	v_add_f32_e32 v88, 1.0, v88
	v_add_f32_e32 v97, 1.0, v97
	v_rcp_f32_e32 v105, v103
	v_add_f32_e32 v103, 1.0, v107
	v_rcp_f32_e32 v88, v88
	v_rcp_f32_e32 v89, v89
	v_rcp_f32_e32 v107, v103
	v_rcp_f32_e32 v103, v97
	v_pk_mul_f32 v[94:95], v[94:95], v[104:105]
	v_pk_mul_f32 v[100:101], v[100:101], v[88:89]
	v_pk_mul_f32 v[90:91], v[90:91], v[106:107]
	v_pk_mul_f32 v[92:93], v[92:93], v[102:103]

; __device__ __forceinline__ float siluf_(float v) { return v * __builtin_amdgcn_rcpf(1.f + __builtin_amdgcn_exp2f(-LOG2E * v)); }
; __device__ __forceinline__ u32x4 pack8(const f32x4& a, const f32x4& b) { u32x4 w; w.x = pk2(a[0], a[1]); w.y = pk2(a[2], a[3]); w.z = pk2(b[0], b[1]); w.w = pk2(b[2], b[3]); return w; }
;     __device__ __forceinline__ void operator()(const AccT& acc, const Unit& u, int wr, int wc, int fr, int fq) const {
;     ...
;             for (int m = 0; m < 4; ++m) { const int row = row0 + ai * 128 + m * 16; const float rs = rsqrtf(rowss[row] * (1.f / DM) + EPS);
; #pragma unroll
;                 for (int bj = 0; bj < 2; ++bj) { f32x4 v0 = acc[ai][bj][m][0] * rs, v1 = acc[ai][bj][m][1] * rs;
;                     if (kind) {
; #pragma unroll
;                         for (int j = 0; j < 4; ++j) { v0[j] = siluf_(v0[j]); v1[j] = siluf_(v1[j]); } }
;                     __builtin_nontemporal_store(pack8(v0, v1), (u32x4*)(base + (size_t)row * BR + col0 + bj * 128)); } }
.LBB0_367:
	v_cvt_pk_bf16_f32 v84, v84, v85
	v_cvt_pk_bf16_f32 v85, v86, v87
	s_nop 0
	v_cvt_pk_bf16_f32 v86, v80, v81
	v_cvt_pk_bf16_f32 v87, v82, v83
	v_or_b32_e32 v82, 48, v148
	v_ashrrev_i32_e32 v83, 31, v82
	global_store_dwordx4 v[88:89], v[84:87], off offset:256 nt
	v_lshl_add_u64 v[80:81], v[82:83], 2, s[50:51]
	v_mov_b32_e32 v80, v235
	s_and_b64 vcc, exec, s[8:9]
	v_fmamk_f32 v80, v80, 0x3a800000, v164
	v_mul_f32_e32 v81, 0x4b800000, v80
	v_cmp_gt_f32_e64 s[10:11], s85, v80
	s_nop 1
	v_cndmask_b32_e64 v80, v80, v81, s[10:11]
	v_rsq_f32_e32 v80, v80
	s_nop 0
	v_mul_f32_e32 v81, 0x45800000, v80
	v_cndmask_b32_e64 v80, v80, v81, s[10:11]
	v_pk_mul_f32 v[78:79], v[78:79], v[80:81] op_sel_hi:[1,0]
	v_pk_mul_f32 v[84:85], v[76:77], v[80:81] op_sel_hi:[1,0]
	v_pk_mul_f32 v[74:75], v[74:75], v[80:81] op_sel_hi:[1,0]
	v_pk_mul_f32 v[76:77], v[72:73], v[80:81] op_sel_hi:[1,0]
	s_cbranch_vccnz .LBB0_369
	v_mul_f32_e32 v87, 0xbfb8aa3b, v78
	v_mul_f32_e32 v73, 0xbfb8aa3b, v76
	v_exp_f32_e32 v87, v87
	v_mul_f32_e32 v88, 0xbfb8aa3b, v74
	v_mul_f32_e32 v81, 0xbfb8aa3b, v85
	v_exp_f32_e32 v73, v73
	v_exp_f32_e32 v89, v88
	v_exp_f32_e32 v81, v81
	v_add_f32_e32 v87, 1.0, v87
	v_add_f32_e32 v73, 1.0, v73
	v_rcp_f32_e32 v88, v87
	v_add_f32_e32 v87, 1.0, v89
	v_mul_f32_e32 v89, 0xbfb8aa3b, v79
	v_mul_f32_e32 v72, 0xbfb8aa3b, v84
	v_rcp_f32_e32 v86, v73
	v_add_f32_e32 v73, 1.0, v81
	v_mul_f32_e32 v81, 0xbfb8aa3b, v77
	v_exp_f32_e32 v89, v89
	v_mul_f32_e32 v90, 0xbfb8aa3b, v75
	v_exp_f32_e32 v72, v72
	v_exp_f32_e32 v81, v81
	v_exp_f32_e32 v91, v90
	v_rcp_f32_e32 v90, v87
	v_add_f32_e32 v87, 1.0, v89
	v_add_f32_e32 v72, 1.0, v72
	v_add_f32_e32 v81, 1.0, v81
	v_rcp_f32_e32 v89, v87
	v_add_f32_e32 v87, 1.0, v91
	v_rcp_f32_e32 v72, v72
	v_rcp_f32_e32 v73, v73
	v_rcp_f32_e32 v91, v87
	v_rcp_f32_e32 v87, v81
	v_pk_mul_f32 v[78:79], v[78:79], v[88:89]
	v_pk_mul_f32 v[84:85], v[84:85], v[72:73]
	v_pk_mul_f32 v[74:75], v[74:75], v[90:91]
	v_pk_mul_f32 v[76:77], v[76:77], v[86:87]

; __device__ __forceinline__ float siluf_(float v) { return v * __builtin_amdgcn_rcpf(1.f + __builtin_amdgcn_exp2f(-LOG2E * v)); }
; __device__ __forceinline__ u32x4 pack8(const f32x4& a, const f32x4& b) { u32x4 w; w.x = pk2(a[0], a[1]); w.y = pk2(a[2], a[3]); w.z = pk2(b[0], b[1]); w.w = pk2(b[2], b[3]); return w; }
;     __device__ __forceinline__ void operator()(const AccT& acc, const Unit& u, int wr, int wc, int fr, int fq) const {
;     ...
;             for (int m = 0; m < 4; ++m) { const int row = row0 + ai * 128 + m * 16; const float rs = rsqrtf(rowss[row] * (1.f / DM) + EPS);
; #pragma unroll
;                 for (int bj = 0; bj < 2; ++bj) { f32x4 v0 = acc[ai][bj][m][0] * rs, v1 = acc[ai][bj][m][1] * rs;
;                     if (kind) {
; #pragma unroll
;                         for (int j = 0; j < 4; ++j) { v0[j] = siluf_(v0[j]); v1[j] = siluf_(v1[j]); } }
;                     __builtin_nontemporal_store(pack8(v0, v1), (u32x4*)(base + (size_t)row * BR + col0 + bj * 128)); } }
.LBB0_371:
	v_cvt_pk_bf16_f32 v68, v68, v69
	v_cvt_pk_bf16_f32 v69, v70, v71
	s_nop 0
	v_cvt_pk_bf16_f32 v70, v64, v65
	v_cvt_pk_bf16_f32 v71, v66, v67
	global_store_dwordx4 v[72:73], v[68:71], off offset:256 nt
	v_mov_b32_e32 v64, v236
	s_and_b64 vcc, exec, s[8:9]
	v_fmamk_f32 v64, v64, 0x3a800000, v164
	v_mul_f32_e32 v65, 0x4b800000, v64
	v_cmp_gt_f32_e64 s[10:11], s85, v64
	s_nop 1
	v_cndmask_b32_e64 v64, v64, v65, s[10:11]
	v_rsq_f32_e32 v64, v64
	s_nop 0
	v_mul_f32_e32 v65, 0x45800000, v64
	v_cndmask_b32_e64 v64, v64, v65, s[10:11]
	v_pk_mul_f32 v[62:63], v[62:63], v[64:65] op_sel_hi:[1,0]
	v_pk_mul_f32 v[66:67], v[60:61], v[64:65] op_sel_hi:[1,0]
	v_pk_mul_f32 v[58:59], v[58:59], v[64:65] op_sel_hi:[1,0]
	v_pk_mul_f32 v[60:61], v[56:57], v[64:65] op_sel_hi:[1,0]
	s_cbranch_vccnz .LBB0_373
	v_mul_f32_e32 v69, 0xbfb8aa3b, v62
	v_mul_f32_e32 v57, 0xbfb8aa3b, v60
	v_exp_f32_e32 v69, v69
	v_mul_f32_e32 v70, 0xbfb8aa3b, v58
	v_mul_f32_e32 v65, 0xbfb8aa3b, v67
	v_exp_f32_e32 v57, v57
	v_exp_f32_e32 v71, v70
	v_exp_f32_e32 v65, v65
	v_add_f32_e32 v69, 1.0, v69
	v_add_f32_e32 v57, 1.0, v57
	v_rcp_f32_e32 v70, v69
	v_add_f32_e32 v69, 1.0, v71
	v_mul_f32_e32 v71, 0xbfb8aa3b, v63
	v_mul_f32_e32 v56, 0xbfb8aa3b, v66
	v_rcp_f32_e32 v68, v57
	v_add_f32_e32 v57, 1.0, v65
	v_mul_f32_e32 v65, 0xbfb8aa3b, v61
	v_exp_f32_e32 v71, v71
	v_mul_f32_e32 v72, 0xbfb8aa3b, v59
	v_exp_f32_e32 v56, v56
	v_exp_f32_e32 v65, v65
	v_exp_f32_e32 v73, v72
	v_rcp_f32_e32 v72, v69
	v_add_f32_e32 v69, 1.0, v71
	v_add_f32_e32 v56, 1.0, v56
	v_add_f32_e32 v65, 1.0, v65
	v_rcp_f32_e32 v71, v69
	v_add_f32_e32 v69, 1.0, v73
	v_rcp_f32_e32 v56, v56
	v_rcp_f32_e32 v57, v57
	v_rcp_f32_e32 v73, v69
	v_rcp_f32_e32 v69, v65
	v_pk_mul_f32 v[62:63], v[62:63], v[70:71]
	v_pk_mul_f32 v[66:67], v[66:67], v[56:57]
	v_pk_mul_f32 v[58:59], v[58:59], v[72:73]
	v_pk_mul_f32 v[60:61], v[60:61], v[68:69]

; __device__ __forceinline__ float siluf_(float v) { return v * __builtin_amdgcn_rcpf(1.f + __builtin_amdgcn_exp2f(-LOG2E * v)); }
; __device__ __forceinline__ u32x4 pack8(const f32x4& a, const f32x4& b) { u32x4 w; w.x = pk2(a[0], a[1]); w.y = pk2(a[2], a[3]); w.z = pk2(b[0], b[1]); w.w = pk2(b[2], b[3]); return w; }
;     __device__ __forceinline__ void operator()(const AccT& acc, const Unit& u, int wr, int wc, int fr, int fq) const {
;     ...
;             for (int m = 0; m < 4; ++m) { const int row = row0 + ai * 128 + m * 16; const float rs = rsqrtf(rowss[row] * (1.f / DM) + EPS);
; #pragma unroll
;                 for (int bj = 0; bj < 2; ++bj) { f32x4 v0 = acc[ai][bj][m][0] * rs, v1 = acc[ai][bj][m][1] * rs;
;                     if (kind) {
; #pragma unroll
;                         for (int j = 0; j < 4; ++j) { v0[j] = siluf_(v0[j]); v1[j] = siluf_(v1[j]); } }
;                     __builtin_nontemporal_store(pack8(v0, v1), (u32x4*)(base + (size_t)row * BR + col0 + bj * 128)); } }
.LBB0_375:
	v_lshl_add_u64 v[56:57], v[56:57], 0, s[22:23]
	v_cvt_pk_bf16_f32 v52, v52, v53
	v_cvt_pk_bf16_f32 v53, v54, v55
	v_cvt_pk_bf16_f32 v54, v48, v49
	v_cvt_pk_bf16_f32 v55, v50, v51
	global_store_dwordx4 v[56:57], v[52:55], off offset:256 nt
	v_mov_b32_e32 v48, v237
	s_and_b64 vcc, exec, s[8:9]
	v_fmamk_f32 v48, v48, 0x3a800000, v164
	v_mul_f32_e32 v49, 0x4b800000, v48
	v_cmp_gt_f32_e64 s[10:11], s85, v48
	s_nop 1
	v_cndmask_b32_e64 v48, v48, v49, s[10:11]
	v_rsq_f32_e32 v48, v48
	s_nop 0
	v_mul_f32_e32 v49, 0x45800000, v48
	v_cndmask_b32_e64 v48, v48, v49, s[10:11]
	v_pk_mul_f32 v[46:47], v[46:47], v[48:49] op_sel_hi:[1,0]
	v_pk_mul_f32 v[50:51], v[44:45], v[48:49] op_sel_hi:[1,0]
	v_pk_mul_f32 v[42:43], v[42:43], v[48:49] op_sel_hi:[1,0]
	v_pk_mul_f32 v[44:45], v[40:41], v[48:49] op_sel_hi:[1,0]
	s_cbranch_vccnz .LBB0_377
	v_mul_f32_e32 v53, 0xbfb8aa3b, v46
	v_mul_f32_e32 v41, 0xbfb8aa3b, v44
	v_exp_f32_e32 v53, v53
	v_mul_f32_e32 v54, 0xbfb8aa3b, v42
	v_mul_f32_e32 v49, 0xbfb8aa3b, v51
	v_exp_f32_e32 v41, v41
	v_exp_f32_e32 v55, v54
	v_exp_f32_e32 v49, v49
	v_add_f32_e32 v53, 1.0, v53
	v_add_f32_e32 v41, 1.0, v41
	v_rcp_f32_e32 v54, v53
	v_add_f32_e32 v53, 1.0, v55
	v_mul_f32_e32 v55, 0xbfb8aa3b, v47
	v_mul_f32_e32 v40, 0xbfb8aa3b, v50
	v_rcp_f32_e32 v52, v41
	v_add_f32_e32 v41, 1.0, v49
	v_mul_f32_e32 v49, 0xbfb8aa3b, v45
	v_exp_f32_e32 v55, v55
	v_mul_f32_e32 v56, 0xbfb8aa3b, v43
	v_exp_f32_e32 v40, v40
	v_exp_f32_e32 v49, v49
	v_exp_f32_e32 v57, v56
	v_rcp_f32_e32 v56, v53
	v_add_f32_e32 v53, 1.0, v55
	v_add_f32_e32 v40, 1.0, v40
	v_add_f32_e32 v49, 1.0, v49
	v_rcp_f32_e32 v55, v53
	v_add_f32_e32 v53, 1.0, v57
	v_rcp_f32_e32 v40, v40
	v_rcp_f32_e32 v41, v41
	v_rcp_f32_e32 v57, v53
	v_rcp_f32_e32 v53, v49
	v_pk_mul_f32 v[46:47], v[46:47], v[54:55]
	v_pk_mul_f32 v[50:51], v[50:51], v[40:41]
	v_pk_mul_f32 v[42:43], v[42:43], v[56:57]
	v_pk_mul_f32 v[44:45], v[44:45], v[52:53]

; __device__ __forceinline__ float siluf_(float v) { return v * __builtin_amdgcn_rcpf(1.f + __builtin_amdgcn_exp2f(-LOG2E * v)); }
; __device__ __forceinline__ u32x4 pack8(const f32x4& a, const f32x4& b) { u32x4 w; w.x = pk2(a[0], a[1]); w.y = pk2(a[2], a[3]); w.z = pk2(b[0], b[1]); w.w = pk2(b[2], b[3]); return w; }
;     __device__ __forceinline__ void operator()(const AccT& acc, const Unit& u, int wr, int wc, int fr, int fq) const {
;     ...
;             for (int m = 0; m < 4; ++m) { const int row = row0 + ai * 128 + m * 16; const float rs = rsqrtf(rowss[row] * (1.f / DM) + EPS);
; #pragma unroll
;                 for (int bj = 0; bj < 2; ++bj) { f32x4 v0 = acc[ai][bj][m][0] * rs, v1 = acc[ai][bj][m][1] * rs;
;                     if (kind) {
; #pragma unroll
;                         for (int j = 0; j < 4; ++j) { v0[j] = siluf_(v0[j]); v1[j] = siluf_(v1[j]); } }
;                     __builtin_nontemporal_store(pack8(v0, v1), (u32x4*)(base + (size_t)row * BR + col0 + bj * 128)); } }
.LBB0_379:
	v_lshl_add_u64 v[40:41], v[40:41], 0, s[40:41]
	v_cvt_pk_bf16_f32 v36, v36, v37
	v_cvt_pk_bf16_f32 v37, v38, v39
	v_cvt_pk_bf16_f32 v38, v32, v33
	v_cvt_pk_bf16_f32 v39, v34, v35
	global_store_dwordx4 v[40:41], v[36:39], off offset:256 nt
	v_mov_b32_e32 v32, v238
	s_and_b64 vcc, exec, s[8:9]
	v_fmamk_f32 v32, v32, 0x3a800000, v164
	v_mul_f32_e32 v33, 0x4b800000, v32
	v_cmp_gt_f32_e64 s[10:11], s85, v32
	s_nop 1
	v_cndmask_b32_e64 v32, v32, v33, s[10:11]
	v_rsq_f32_e32 v32, v32
	s_nop 0
	v_mul_f32_e32 v33, 0x45800000, v32
	v_cndmask_b32_e64 v32, v32, v33, s[10:11]
	v_pk_mul_f32 v[30:31], v[30:31], v[32:33] op_sel_hi:[1,0]
	v_pk_mul_f32 v[34:35], v[28:29], v[32:33] op_sel_hi:[1,0]
	v_pk_mul_f32 v[26:27], v[26:27], v[32:33] op_sel_hi:[1,0]
	v_pk_mul_f32 v[28:29], v[24:25], v[32:33] op_sel_hi:[1,0]
	s_cbranch_vccnz .LBB0_381
	v_mul_f32_e32 v37, 0xbfb8aa3b, v30
	v_mul_f32_e32 v25, 0xbfb8aa3b, v28
	v_exp_f32_e32 v37, v37
	v_mul_f32_e32 v38, 0xbfb8aa3b, v26
	v_mul_f32_e32 v33, 0xbfb8aa3b, v35
	v_exp_f32_e32 v25, v25
	v_exp_f32_e32 v39, v38
	v_exp_f32_e32 v33, v33
	v_add_f32_e32 v37, 1.0, v37
	v_add_f32_e32 v25, 1.0, v25
	v_rcp_f32_e32 v38, v37
	v_add_f32_e32 v37, 1.0, v39
	v_mul_f32_e32 v39, 0xbfb8aa3b, v31
	v_mul_f32_e32 v24, 0xbfb8aa3b, v34
	v_rcp_f32_e32 v36, v25
	v_add_f32_e32 v25, 1.0, v33
	v_mul_f32_e32 v33, 0xbfb8aa3b, v29
	v_exp_f32_e32 v39, v39
	v_mul_f32_e32 v40, 0xbfb8aa3b, v27
	v_exp_f32_e32 v24, v24
	v_exp_f32_e32 v33, v33
	v_exp_f32_e32 v41, v40
	v_rcp_f32_e32 v40, v37
	v_add_f32_e32 v37, 1.0, v39
	v_add_f32_e32 v24, 1.0, v24
	v_add_f32_e32 v33, 1.0, v33
	v_rcp_f32_e32 v39, v37
	v_add_f32_e32 v37, 1.0, v41
	v_rcp_f32_e32 v24, v24
	v_rcp_f32_e32 v25, v25
	v_rcp_f32_e32 v41, v37
	v_rcp_f32_e32 v37, v33
	v_pk_mul_f32 v[30:31], v[30:31], v[38:39]
	v_pk_mul_f32 v[34:35], v[34:35], v[24:25]
	v_pk_mul_f32 v[26:27], v[26:27], v[40:41]
	v_pk_mul_f32 v[28:29], v[28:29], v[36:37]

; __device__ __forceinline__ float siluf_(float v) { return v * __builtin_amdgcn_rcpf(1.f + __builtin_amdgcn_exp2f(-LOG2E * v)); }
; __device__ __forceinline__ u32x4 pack8(const f32x4& a, const f32x4& b) { u32x4 w; w.x = pk2(a[0], a[1]); w.y = pk2(a[2], a[3]); w.z = pk2(b[0], b[1]); w.w = pk2(b[2], b[3]); return w; }
;     __device__ __forceinline__ void operator()(const AccT& acc, const Unit& u, int wr, int wc, int fr, int fq) const {
;     ...
;             for (int m = 0; m < 4; ++m) { const int row = row0 + ai * 128 + m * 16; const float rs = rsqrtf(rowss[row] * (1.f / DM) + EPS);
; #pragma unroll
;                 for (int bj = 0; bj < 2; ++bj) { f32x4 v0 = acc[ai][bj][m][0] * rs, v1 = acc[ai][bj][m][1] * rs;
;                     if (kind) {
; #pragma unroll
;                         for (int j = 0; j < 4; ++j) { v0[j] = siluf_(v0[j]); v1[j] = siluf_(v1[j]); } }
;                     __builtin_nontemporal_store(pack8(v0, v1), (u32x4*)(base + (size_t)row * BR + col0 + bj * 128)); } }
.LBB0_383:
	v_lshl_add_u64 v[24:25], v[24:25], 0, s[42:43]
	v_cvt_pk_bf16_f32 v20, v20, v21
	v_cvt_pk_bf16_f32 v21, v22, v23
	v_cvt_pk_bf16_f32 v22, v16, v17
	v_cvt_pk_bf16_f32 v23, v18, v19
	global_store_dwordx4 v[24:25], v[20:23], off offset:256 nt
	v_mov_b32_e32 v16, v239
	s_and_b64 vcc, exec, s[8:9]
	v_fmamk_f32 v16, v16, 0x3a800000, v164
	v_mul_f32_e32 v17, 0x4b800000, v16
	v_cmp_gt_f32_e64 s[10:11], s85, v16
	s_nop 1
	v_cndmask_b32_e64 v16, v16, v17, s[10:11]
	v_rsq_f32_e32 v16, v16
	s_nop 0
	v_mul_f32_e32 v17, 0x45800000, v16
	v_cndmask_b32_e64 v16, v16, v17, s[10:11]
	v_pk_mul_f32 v[14:15], v[14:15], v[16:17] op_sel_hi:[1,0]
	v_pk_mul_f32 v[18:19], v[12:13], v[16:17] op_sel_hi:[1,0]
	v_pk_mul_f32 v[10:11], v[10:11], v[16:17] op_sel_hi:[1,0]
	v_pk_mul_f32 v[12:13], v[8:9], v[16:17] op_sel_hi:[1,0]
	s_cbranch_vccnz .LBB0_385
	v_mul_f32_e32 v21, 0xbfb8aa3b, v14
	v_mul_f32_e32 v9, 0xbfb8aa3b, v12
	v_exp_f32_e32 v21, v21
	v_mul_f32_e32 v22, 0xbfb8aa3b, v10
	v_mul_f32_e32 v17, 0xbfb8aa3b, v19
	v_exp_f32_e32 v9, v9
	v_exp_f32_e32 v23, v22
	v_exp_f32_e32 v17, v17
	v_add_f32_e32 v21, 1.0, v21
	v_add_f32_e32 v9, 1.0, v9
	v_rcp_f32_e32 v22, v21
	v_add_f32_e32 v21, 1.0, v23
	v_mul_f32_e32 v23, 0xbfb8aa3b, v15
	v_mul_f32_e32 v8, 0xbfb8aa3b, v18
	v_rcp_f32_e32 v20, v9
	v_add_f32_e32 v9, 1.0, v17
	v_mul_f32_e32 v17, 0xbfb8aa3b, v13
	v_exp_f32_e32 v23, v23
	v_mul_f32_e32 v24, 0xbfb8aa3b, v11
	v_exp_f32_e32 v8, v8
	v_exp_f32_e32 v17, v17
	v_exp_f32_e32 v25, v24
	v_rcp_f32_e32 v24, v21
	v_add_f32_e32 v21, 1.0, v23
	v_add_f32_e32 v8, 1.0, v8
	v_add_f32_e32 v17, 1.0, v17
	v_rcp_f32_e32 v23, v21
	v_add_f32_e32 v21, 1.0, v25
	v_rcp_f32_e32 v8, v8
	v_rcp_f32_e32 v9, v9
	v_rcp_f32_e32 v25, v21
	v_rcp_f32_e32 v21, v17
	v_pk_mul_f32 v[14:15], v[14:15], v[22:23]
	v_pk_mul_f32 v[18:19], v[18:19], v[8:9]
	v_pk_mul_f32 v[10:11], v[10:11], v[24:25]
	v_pk_mul_f32 v[12:13], v[12:13], v[20:21]
